# accstat + no setprio + merged pre-barrier waits and redundant post-barrier lgkmcnt(0) removed in GEMM loops
# speedup vs baseline: 1.0173x; 1.0022x over previous
.LBB0_101:
	ds_read_b128 v[154:157], v151
	ds_read_b128 v[158:161], v151 offset:1024
	ds_read_b128 v[162:165], v151 offset:2048
	ds_read_b128 v[166:169], v151 offset:3072
	ds_read_b128 v[170:173], v152
	ds_read_b128 v[174:177], v152 offset:1024
	ds_read_b128 v[188:191], v152 offset:2048
	ds_read_b128 v[192:195], v152 offset:3072
	s_add_u32 s40, s36, s38
	s_addc_u32 s41, s37, s39
	s_add_u32 s44, s40, 0x100
	s_addc_u32 s45, s41, 0
	s_add_u32 s42, s66, s38
	s_addc_u32 s43, s67, s39
	s_add_u32 s40, s40, 0x180
	s_addc_u32 s41, s41, 0
	s_cmpk_eq_i32 s38, 0x1f00
	s_cselect_b32 s41, s65, s41
	s_cselect_b32 s40, s64, s40
	s_cselect_b32 s43, s35, s43
	s_cselect_b32 s42, s34, s42
	s_cselect_b32 s45, s23, s45
	s_cselect_b32 s44, s22, s44
	s_mov_b32 m0, s57
	v_lshl_add_u64 v[178:179], v[146:147], 0, s[38:39]
	ds_read_b128 v[196:199], v153
	ds_read_b128 v[200:203], v153 offset:1024
	ds_read_b128 v[204:207], v153 offset:2048
	ds_read_b128 v[208:211], v153 offset:3072
	ds_read_b128 v[214:217], v153 offset:4096
	ds_read_b128 v[218:221], v153 offset:5120
	ds_read_b128 v[222:225], v153 offset:6144
	ds_read_b128 v[226:229], v153 offset:7168
	global_load_lds_dwordx4 v[178:179], off
	v_lshl_add_u64 v[178:179], v[148:149], 0, s[38:39]
	s_add_i32 m0, s47, 0xe000
	s_nop 0
	global_load_lds_dwordx4 v[178:179], off
	s_waitcnt vmcnt(8) lgkmcnt(0)
	s_barrier
	v_mfma_f32_16x16x32_bf16 v[126:129], v[154:157], v[196:199], v[126:129]
	v_mfma_f32_16x16x32_bf16 v[126:129], v[158:161], v[200:203], v[126:129]
	v_mfma_f32_16x16x32_bf16 v[122:125], v[162:165], v[196:199], v[122:125]
	v_mfma_f32_16x16x32_bf16 v[122:125], v[166:169], v[200:203], v[122:125]
	v_mfma_f32_16x16x32_bf16 v[118:121], v[154:157], v[204:207], v[118:121]
	v_mfma_f32_16x16x32_bf16 v[118:121], v[158:161], v[208:211], v[118:121]
	v_mfma_f32_16x16x32_bf16 v[110:113], v[162:165], v[204:207], v[110:113]
	v_mfma_f32_16x16x32_bf16 v[110:113], v[166:169], v[208:211], v[110:113]
	v_mfma_f32_16x16x32_bf16 v[102:105], v[154:157], v[214:217], v[102:105]
	v_mfma_f32_16x16x32_bf16 v[102:105], v[158:161], v[218:221], v[102:105]
	v_mfma_f32_16x16x32_bf16 v[94:97], v[162:165], v[214:217], v[94:97]
	v_mfma_f32_16x16x32_bf16 v[94:97], v[166:169], v[218:221], v[94:97]
	v_mfma_f32_16x16x32_bf16 v[86:89], v[154:157], v[222:225], v[86:89]
	v_mfma_f32_16x16x32_bf16 v[86:89], v[158:161], v[226:229], v[86:89]
	v_mfma_f32_16x16x32_bf16 v[78:81], v[162:165], v[222:225], v[78:81]
	v_mfma_f32_16x16x32_bf16 v[78:81], v[166:169], v[226:229], v[78:81]
	v_mfma_f32_16x16x32_bf16 v[114:117], v[170:173], v[196:199], v[114:117]
	v_mfma_f32_16x16x32_bf16 v[114:117], v[174:177], v[200:203], v[114:117]
	v_mfma_f32_16x16x32_bf16 v[106:109], v[188:191], v[196:199], v[106:109]
	v_mfma_f32_16x16x32_bf16 v[106:109], v[192:195], v[200:203], v[106:109]
	v_mfma_f32_16x16x32_bf16 v[98:101], v[170:173], v[204:207], v[98:101]
	v_mfma_f32_16x16x32_bf16 v[98:101], v[174:177], v[208:211], v[98:101]
	v_mfma_f32_16x16x32_bf16 v[90:93], v[188:191], v[204:207], v[90:93]
	v_mfma_f32_16x16x32_bf16 v[90:93], v[192:195], v[208:211], v[90:93]
	v_mfma_f32_16x16x32_bf16 v[82:85], v[170:173], v[214:217], v[82:85]
	v_mfma_f32_16x16x32_bf16 v[82:85], v[174:177], v[218:221], v[82:85]
	v_mfma_f32_16x16x32_bf16 v[74:77], v[188:191], v[214:217], v[74:77]
	v_mfma_f32_16x16x32_bf16 v[74:77], v[192:195], v[218:221], v[74:77]
	v_mfma_f32_16x16x32_bf16 v[70:73], v[170:173], v[222:225], v[70:73]
	v_mfma_f32_16x16x32_bf16 v[70:73], v[174:177], v[226:229], v[70:73]
	v_mfma_f32_16x16x32_bf16 v[66:69], v[188:191], v[222:225], v[66:69]
	v_mfma_f32_16x16x32_bf16 v[66:69], v[192:195], v[226:229], v[66:69]
	s_barrier
	s_add_i32 s69, s54, s3
	v_lshl_add_u64 v[178:179], s[42:43], 0, v[136:137]
	s_mov_b32 m0, s69
	ds_read_b128 v[196:199], v153 offset:16384
	ds_read_b128 v[200:203], v153 offset:17408
	ds_read_b128 v[204:207], v153 offset:18432
	ds_read_b128 v[208:211], v153 offset:19456
	ds_read_b128 v[214:217], v153 offset:20480
	ds_read_b128 v[218:221], v153 offset:21504
	ds_read_b128 v[222:225], v153 offset:22528
	ds_read_b128 v[226:229], v153 offset:23552
	global_load_lds_dwordx4 v[178:179], off
	s_add_i32 m0, s69, 0x2000
	s_add_u32 s70, s42, 0x108000
	v_lshl_add_u64 v[230:231], s[42:43], 0, v[140:141]
	s_addc_u32 s71, s43, 0
	s_add_i32 s69, s55, s3
	global_load_lds_dwordx4 v[230:231], off
	v_lshl_add_u64 v[232:233], s[70:71], 0, v[136:137]
	s_mov_b32 m0, s69
	s_nop 0
	global_load_lds_dwordx4 v[232:233], off
	v_lshl_add_u64 v[232:233], s[70:71], 0, v[140:141]
	s_add_i32 m0, s69, 0x2000
	s_nop 0
	global_load_lds_dwordx4 v[232:233], off
	v_lshl_add_u64 v[232:233], s[44:45], 0, v[134:135]
	s_mov_b32 m0, s47
	s_nop 0
	global_load_lds_dwordx4 v[232:233], off
	v_lshl_add_u64 v[232:233], s[44:45], 0, v[138:139]
	s_mov_b32 m0, s48
	s_nop 0
	global_load_lds_dwordx4 v[232:233], off
	s_waitcnt vmcnt(8) lgkmcnt(0)
	s_barrier
	v_mfma_f32_16x16x32_bf16 v[62:65], v[154:157], v[196:199], v[62:65]
	v_mfma_f32_16x16x32_bf16 v[62:65], v[158:161], v[200:203], v[62:65]
	v_mfma_f32_16x16x32_bf16 v[58:61], v[162:165], v[196:199], v[58:61]
	v_mfma_f32_16x16x32_bf16 v[58:61], v[166:169], v[200:203], v[58:61]
	v_mfma_f32_16x16x32_bf16 v[54:57], v[154:157], v[204:207], v[54:57]
	v_mfma_f32_16x16x32_bf16 v[54:57], v[158:161], v[208:211], v[54:57]
	v_mfma_f32_16x16x32_bf16 v[46:49], v[162:165], v[204:207], v[46:49]
	v_mfma_f32_16x16x32_bf16 v[46:49], v[166:169], v[208:211], v[46:49]
	v_mfma_f32_16x16x32_bf16 v[38:41], v[154:157], v[214:217], v[38:41]
	v_mfma_f32_16x16x32_bf16 v[38:41], v[158:161], v[218:221], v[38:41]
	v_mfma_f32_16x16x32_bf16 v[30:33], v[162:165], v[214:217], v[30:33]
	v_mfma_f32_16x16x32_bf16 v[30:33], v[166:169], v[218:221], v[30:33]
	v_mfma_f32_16x16x32_bf16 v[22:25], v[154:157], v[222:225], v[22:25]
	v_mfma_f32_16x16x32_bf16 v[22:25], v[158:161], v[226:229], v[22:25]
	v_mfma_f32_16x16x32_bf16 v[14:17], v[162:165], v[222:225], v[14:17]
	v_mfma_f32_16x16x32_bf16 v[14:17], v[166:169], v[226:229], v[14:17]
	v_mfma_f32_16x16x32_bf16 v[50:53], v[170:173], v[196:199], v[50:53]
	v_mfma_f32_16x16x32_bf16 v[50:53], v[174:177], v[200:203], v[50:53]
	v_mfma_f32_16x16x32_bf16 v[42:45], v[188:191], v[196:199], v[42:45]
	v_mfma_f32_16x16x32_bf16 v[42:45], v[192:195], v[200:203], v[42:45]
	v_mfma_f32_16x16x32_bf16 v[34:37], v[170:173], v[204:207], v[34:37]
	v_mfma_f32_16x16x32_bf16 v[34:37], v[174:177], v[208:211], v[34:37]
	v_mfma_f32_16x16x32_bf16 v[26:29], v[188:191], v[204:207], v[26:29]
	v_mfma_f32_16x16x32_bf16 v[26:29], v[192:195], v[208:211], v[26:29]
	v_mfma_f32_16x16x32_bf16 v[18:21], v[170:173], v[214:217], v[18:21]
	v_mfma_f32_16x16x32_bf16 v[18:21], v[174:177], v[218:221], v[18:21]
	v_mfma_f32_16x16x32_bf16 v[10:13], v[188:191], v[214:217], v[10:13]
	v_mfma_f32_16x16x32_bf16 v[10:13], v[192:195], v[218:221], v[10:13]
	v_mfma_f32_16x16x32_bf16 v[6:9], v[170:173], v[222:225], v[6:9]
	v_mfma_f32_16x16x32_bf16 v[6:9], v[174:177], v[226:229], v[6:9]
	v_mfma_f32_16x16x32_bf16 v[2:5], v[188:191], v[222:225], v[2:5]
	v_mfma_f32_16x16x32_bf16 v[2:5], v[192:195], v[226:229], v[2:5]
	s_barrier
	s_add_i32 s69, 0, 0x18000
	s_add_i32 s70, 0, 0x1c000
	v_add_u32_e32 v166, s69, v133
	v_add_u32_e32 v187, s70, v133
	ds_read_b128 v[154:157], v166
	ds_read_b128 v[158:161], v166 offset:1024
	ds_read_b128 v[162:165], v166 offset:2048
	ds_read_b128 v[166:169], v166 offset:3072
	ds_read_b128 v[170:173], v187
	ds_read_b128 v[174:177], v187 offset:1024
	ds_read_b128 v[188:191], v187 offset:2048
	ds_read_b128 v[192:195], v187 offset:3072
	s_add_u32 s44, s44, 0x108000
	s_addc_u32 s45, s45, 0
	s_mov_b32 m0, s49
	v_lshl_add_u64 v[232:233], s[44:45], 0, v[134:135]
	ds_read_b128 v[196:199], v153 offset:32768
	ds_read_b128 v[200:203], v153 offset:33792
	ds_read_b128 v[204:207], v153 offset:34816
	ds_read_b128 v[208:211], v153 offset:35840
	ds_read_b128 v[214:217], v153 offset:36864
	ds_read_b128 v[218:221], v153 offset:37888
	ds_read_b128 v[222:225], v153 offset:38912
	ds_read_b128 v[226:229], v153 offset:39936
	global_load_lds_dwordx4 v[232:233], off
	v_lshl_add_u64 v[232:233], s[44:45], 0, v[138:139]
	s_mov_b32 m0, s50
	s_nop 0
	global_load_lds_dwordx4 v[232:233], off
	s_waitcnt vmcnt(8) lgkmcnt(0)
	s_barrier
	v_mfma_f32_16x16x32_bf16 v[126:129], v[154:157], v[196:199], v[126:129]
	v_mfma_f32_16x16x32_bf16 v[126:129], v[158:161], v[200:203], v[126:129]
	v_mfma_f32_16x16x32_bf16 v[122:125], v[162:165], v[196:199], v[122:125]
	v_mfma_f32_16x16x32_bf16 v[122:125], v[166:169], v[200:203], v[122:125]
	v_mfma_f32_16x16x32_bf16 v[118:121], v[154:157], v[204:207], v[118:121]
	v_mfma_f32_16x16x32_bf16 v[118:121], v[158:161], v[208:211], v[118:121]
	v_mfma_f32_16x16x32_bf16 v[110:113], v[162:165], v[204:207], v[110:113]
	v_mfma_f32_16x16x32_bf16 v[110:113], v[166:169], v[208:211], v[110:113]
	v_mfma_f32_16x16x32_bf16 v[102:105], v[154:157], v[214:217], v[102:105]
	v_mfma_f32_16x16x32_bf16 v[102:105], v[158:161], v[218:221], v[102:105]
	v_mfma_f32_16x16x32_bf16 v[94:97], v[162:165], v[214:217], v[94:97]
	v_mfma_f32_16x16x32_bf16 v[94:97], v[166:169], v[218:221], v[94:97]
	v_mfma_f32_16x16x32_bf16 v[86:89], v[154:157], v[222:225], v[86:89]
	v_mfma_f32_16x16x32_bf16 v[86:89], v[158:161], v[226:229], v[86:89]
	v_mfma_f32_16x16x32_bf16 v[78:81], v[162:165], v[222:225], v[78:81]
	v_mfma_f32_16x16x32_bf16 v[78:81], v[166:169], v[226:229], v[78:81]
	v_mfma_f32_16x16x32_bf16 v[114:117], v[170:173], v[196:199], v[114:117]
	v_mfma_f32_16x16x32_bf16 v[114:117], v[174:177], v[200:203], v[114:117]
	v_mfma_f32_16x16x32_bf16 v[106:109], v[188:191], v[196:199], v[106:109]
	v_mfma_f32_16x16x32_bf16 v[106:109], v[192:195], v[200:203], v[106:109]
	v_mfma_f32_16x16x32_bf16 v[98:101], v[170:173], v[204:207], v[98:101]
	v_mfma_f32_16x16x32_bf16 v[98:101], v[174:177], v[208:211], v[98:101]
	v_mfma_f32_16x16x32_bf16 v[90:93], v[188:191], v[204:207], v[90:93]
	v_mfma_f32_16x16x32_bf16 v[90:93], v[192:195], v[208:211], v[90:93]
	v_mfma_f32_16x16x32_bf16 v[82:85], v[170:173], v[214:217], v[82:85]
	v_mfma_f32_16x16x32_bf16 v[82:85], v[174:177], v[218:221], v[82:85]
	v_mfma_f32_16x16x32_bf16 v[74:77], v[188:191], v[214:217], v[74:77]
	v_mfma_f32_16x16x32_bf16 v[74:77], v[192:195], v[218:221], v[74:77]
	v_mfma_f32_16x16x32_bf16 v[70:73], v[170:173], v[222:225], v[70:73]
	v_mfma_f32_16x16x32_bf16 v[70:73], v[174:177], v[226:229], v[70:73]
	v_mfma_f32_16x16x32_bf16 v[66:69], v[188:191], v[222:225], v[66:69]
	v_mfma_f32_16x16x32_bf16 v[66:69], v[192:195], v[226:229], v[66:69]
	s_barrier
	s_add_i32 s44, s69, s3
	v_lshl_add_u64 v[178:179], v[178:179], 0, s[12:13]
	s_mov_b32 m0, s44
	ds_read_b128 v[196:199], v153 offset:49152
	ds_read_b128 v[200:203], v153 offset:50176
	ds_read_b128 v[204:207], v153 offset:51200
	ds_read_b128 v[208:211], v153 offset:52224
	ds_read_b128 v[214:217], v153 offset:53248
	ds_read_b128 v[218:221], v153 offset:54272
	ds_read_b128 v[222:225], v153 offset:55296
	ds_read_b128 v[226:229], v153 offset:56320
	global_load_lds_dwordx4 v[178:179], off
	s_add_i32 m0, s44, 0x2000
	s_add_u32 s42, s42, 0x108080
	v_lshl_add_u64 v[178:179], v[230:231], 0, s[12:13]
	s_addc_u32 s43, s43, 0
	s_add_i32 s44, s70, s3
	global_load_lds_dwordx4 v[178:179], off
	v_lshl_add_u64 v[178:179], s[42:43], 0, v[136:137]
	s_mov_b32 m0, s44
	s_nop 0
	global_load_lds_dwordx4 v[178:179], off
	v_lshl_add_u64 v[178:179], s[42:43], 0, v[140:141]
	s_add_i32 m0, s44, 0x2000
	s_nop 0
	global_load_lds_dwordx4 v[178:179], off
	v_lshl_add_u64 v[178:179], s[40:41], 0, v[134:135]
	s_mov_b32 m0, s52
	s_nop 0
	global_load_lds_dwordx4 v[178:179], off
	v_lshl_add_u64 v[178:179], s[40:41], 0, v[138:139]
	s_mov_b32 m0, s53
	s_nop 0
	global_load_lds_dwordx4 v[178:179], off
	s_waitcnt vmcnt(8) lgkmcnt(0)
	s_barrier
	v_mfma_f32_16x16x32_bf16 v[62:65], v[154:157], v[196:199], v[62:65]
	v_mfma_f32_16x16x32_bf16 v[62:65], v[158:161], v[200:203], v[62:65]
	v_mfma_f32_16x16x32_bf16 v[58:61], v[162:165], v[196:199], v[58:61]
	v_mfma_f32_16x16x32_bf16 v[58:61], v[166:169], v[200:203], v[58:61]
	v_mfma_f32_16x16x32_bf16 v[54:57], v[154:157], v[204:207], v[54:57]
	v_mfma_f32_16x16x32_bf16 v[54:57], v[158:161], v[208:211], v[54:57]
	v_mfma_f32_16x16x32_bf16 v[46:49], v[162:165], v[204:207], v[46:49]
	v_mfma_f32_16x16x32_bf16 v[46:49], v[166:169], v[208:211], v[46:49]
	v_mfma_f32_16x16x32_bf16 v[38:41], v[154:157], v[214:217], v[38:41]
	v_mfma_f32_16x16x32_bf16 v[38:41], v[158:161], v[218:221], v[38:41]
	v_mfma_f32_16x16x32_bf16 v[30:33], v[162:165], v[214:217], v[30:33]
	v_mfma_f32_16x16x32_bf16 v[30:33], v[166:169], v[218:221], v[30:33]
	v_mfma_f32_16x16x32_bf16 v[22:25], v[154:157], v[222:225], v[22:25]
	v_mfma_f32_16x16x32_bf16 v[22:25], v[158:161], v[226:229], v[22:25]
	v_mfma_f32_16x16x32_bf16 v[14:17], v[162:165], v[222:225], v[14:17]
	v_mfma_f32_16x16x32_bf16 v[14:17], v[166:169], v[226:229], v[14:17]
	v_mfma_f32_16x16x32_bf16 v[50:53], v[170:173], v[196:199], v[50:53]
	v_mfma_f32_16x16x32_bf16 v[50:53], v[174:177], v[200:203], v[50:53]
	v_mfma_f32_16x16x32_bf16 v[42:45], v[188:191], v[196:199], v[42:45]
	v_mfma_f32_16x16x32_bf16 v[42:45], v[192:195], v[200:203], v[42:45]
	v_mfma_f32_16x16x32_bf16 v[34:37], v[170:173], v[204:207], v[34:37]
	v_mfma_f32_16x16x32_bf16 v[34:37], v[174:177], v[208:211], v[34:37]
	v_mfma_f32_16x16x32_bf16 v[26:29], v[188:191], v[204:207], v[26:29]
	v_mfma_f32_16x16x32_bf16 v[26:29], v[192:195], v[208:211], v[26:29]
	v_mfma_f32_16x16x32_bf16 v[18:21], v[170:173], v[214:217], v[18:21]
	v_mfma_f32_16x16x32_bf16 v[18:21], v[174:177], v[218:221], v[18:21]
	v_mfma_f32_16x16x32_bf16 v[10:13], v[188:191], v[214:217], v[10:13]
	v_mfma_f32_16x16x32_bf16 v[10:13], v[192:195], v[218:221], v[10:13]
	v_mfma_f32_16x16x32_bf16 v[6:9], v[170:173], v[222:225], v[6:9]
	v_mfma_f32_16x16x32_bf16 v[6:9], v[174:177], v[226:229], v[6:9]
	v_mfma_f32_16x16x32_bf16 v[2:5], v[188:191], v[222:225], v[2:5]
	v_mfma_f32_16x16x32_bf16 v[2:5], v[192:195], v[226:229], v[2:5]
	s_barrier
	s_add_i32 s68, s68, 2
	s_add_u32 s38, s38, 0x100
	s_addc_u32 s39, s39, 0
	s_cmp_gt_u32 s68, 61
	s_cbranch_scc0 .LBB0_101
	s_and_b64 vcc, exec, s[20:21]
	s_cbranch_vccz .LBB0_104
	s_barrier

.LBB0_235:
	ds_read_b128 v[156:159], v150
	ds_read_b128 v[160:163], v150 offset:1024
	ds_read_b128 v[164:167], v150 offset:2048
	ds_read_b128 v[168:171], v150 offset:3072
	ds_read_b128 v[172:175], v151
	ds_read_b128 v[176:179], v151 offset:1024
	ds_read_b128 v[180:183], v151 offset:2048
	ds_read_b128 v[184:187], v151 offset:3072
	s_add_u32 s36, s4, s34
	s_addc_u32 s37, s5, s35
	s_add_u32 s40, s36, 0x100
	s_addc_u32 s41, s37, 0
	s_add_u32 s38, s62, s34
	s_addc_u32 s39, s63, s35
	s_add_u32 s36, s36, 0x180
	s_addc_u32 s37, s37, 0
	s_cmpk_eq_i32 s34, 0x1f00
	s_cselect_b32 s37, s61, s37
	s_cselect_b32 s36, s60, s36
	s_cselect_b32 s39, s31, s39
	s_cselect_b32 s38, s30, s38
	s_cselect_b32 s41, s23, s41
	s_cselect_b32 s40, s22, s40
	s_mov_b32 m0, s46
	v_lshl_add_u64 v[222:223], v[146:147], 0, s[34:35]
	ds_read_b128 v[188:191], v152
	ds_read_b128 v[192:195], v152 offset:1024
	ds_read_b128 v[196:199], v152 offset:2048
	ds_read_b128 v[200:203], v152 offset:3072
	ds_read_b128 v[204:207], v152 offset:4096
	ds_read_b128 v[208:211], v152 offset:5120
	ds_read_b128 v[214:217], v152 offset:6144
	ds_read_b128 v[218:221], v152 offset:7168
	global_load_lds_dwordx4 v[222:223], off
	v_lshl_add_u64 v[222:223], v[148:149], 0, s[34:35]
	s_mov_b32 m0, s47
	s_nop 0
	global_load_lds_dwordx4 v[222:223], off
	s_waitcnt vmcnt(8) lgkmcnt(0)
	s_barrier
	v_mfma_f32_16x16x32_bf16 v[126:129], v[156:159], v[188:191], v[126:129]
	v_mfma_f32_16x16x32_bf16 v[126:129], v[160:163], v[192:195], v[126:129]
	v_mfma_f32_16x16x32_bf16 v[122:125], v[164:167], v[188:191], v[122:125]
	v_mfma_f32_16x16x32_bf16 v[122:125], v[168:171], v[192:195], v[122:125]
	v_mfma_f32_16x16x32_bf16 v[110:113], v[156:159], v[196:199], v[110:113]
	v_mfma_f32_16x16x32_bf16 v[110:113], v[160:163], v[200:203], v[110:113]
	v_mfma_f32_16x16x32_bf16 v[106:109], v[164:167], v[196:199], v[106:109]
	v_mfma_f32_16x16x32_bf16 v[106:109], v[168:171], v[200:203], v[106:109]
	v_mfma_f32_16x16x32_bf16 v[94:97], v[156:159], v[204:207], v[94:97]
	v_mfma_f32_16x16x32_bf16 v[94:97], v[160:163], v[208:211], v[94:97]
	v_mfma_f32_16x16x32_bf16 v[90:93], v[164:167], v[204:207], v[90:93]
	v_mfma_f32_16x16x32_bf16 v[90:93], v[168:171], v[208:211], v[90:93]
	v_mfma_f32_16x16x32_bf16 v[78:81], v[156:159], v[214:217], v[78:81]
	v_mfma_f32_16x16x32_bf16 v[78:81], v[160:163], v[218:221], v[78:81]
	v_mfma_f32_16x16x32_bf16 v[74:77], v[164:167], v[214:217], v[74:77]
	v_mfma_f32_16x16x32_bf16 v[74:77], v[168:171], v[218:221], v[74:77]
	v_mfma_f32_16x16x32_bf16 v[118:121], v[172:175], v[188:191], v[118:121]
	v_mfma_f32_16x16x32_bf16 v[118:121], v[176:179], v[192:195], v[118:121]
	v_mfma_f32_16x16x32_bf16 v[114:117], v[180:183], v[188:191], v[114:117]
	v_mfma_f32_16x16x32_bf16 v[114:117], v[184:187], v[192:195], v[114:117]
	v_mfma_f32_16x16x32_bf16 v[102:105], v[172:175], v[196:199], v[102:105]
	v_mfma_f32_16x16x32_bf16 v[102:105], v[176:179], v[200:203], v[102:105]
	v_mfma_f32_16x16x32_bf16 v[98:101], v[180:183], v[196:199], v[98:101]
	v_mfma_f32_16x16x32_bf16 v[98:101], v[184:187], v[200:203], v[98:101]
	v_mfma_f32_16x16x32_bf16 v[86:89], v[172:175], v[204:207], v[86:89]
	v_mfma_f32_16x16x32_bf16 v[86:89], v[176:179], v[208:211], v[86:89]
	v_mfma_f32_16x16x32_bf16 v[82:85], v[180:183], v[204:207], v[82:85]
	v_mfma_f32_16x16x32_bf16 v[82:85], v[184:187], v[208:211], v[82:85]
	v_mfma_f32_16x16x32_bf16 v[70:73], v[172:175], v[214:217], v[70:73]
	v_mfma_f32_16x16x32_bf16 v[70:73], v[176:179], v[218:221], v[70:73]
	v_mfma_f32_16x16x32_bf16 v[66:69], v[180:183], v[214:217], v[66:69]
	v_mfma_f32_16x16x32_bf16 v[66:69], v[184:187], v[218:221], v[66:69]
	s_barrier
	s_mov_b32 m0, s48
	v_lshl_add_u64 v[222:223], s[38:39], 0, v[132:133]
	s_add_u32 s66, s38, 0x108000
	ds_read_b128 v[188:191], v152 offset:16384
	ds_read_b128 v[192:195], v152 offset:17408
	ds_read_b128 v[196:199], v152 offset:18432
	ds_read_b128 v[200:203], v152 offset:19456
	ds_read_b128 v[204:207], v152 offset:20480
	ds_read_b128 v[208:211], v152 offset:21504
	ds_read_b128 v[214:217], v152 offset:22528
	ds_read_b128 v[218:221], v152 offset:23552
	global_load_lds_dwordx4 v[222:223], off
	v_lshl_add_u64 v[224:225], s[38:39], 0, v[136:137]
	s_mov_b32 m0, s49
	s_addc_u32 s67, s39, 0
	global_load_lds_dwordx4 v[224:225], off
	v_lshl_add_u64 v[226:227], s[66:67], 0, v[132:133]
	s_mov_b32 m0, s50
	s_nop 0
	global_load_lds_dwordx4 v[226:227], off
	v_lshl_add_u64 v[226:227], s[66:67], 0, v[136:137]
	s_mov_b32 m0, s51
	s_nop 0
	global_load_lds_dwordx4 v[226:227], off
	v_lshl_add_u64 v[226:227], s[40:41], 0, v[130:131]
	s_mov_b32 m0, s3
	s_nop 0
	global_load_lds_dwordx4 v[226:227], off
	v_lshl_add_u64 v[226:227], s[40:41], 0, v[134:135]
	s_mov_b32 m0, s33
	s_nop 0
	global_load_lds_dwordx4 v[226:227], off
	s_waitcnt vmcnt(8) lgkmcnt(0)
	s_barrier
	v_mfma_f32_16x16x32_bf16 v[62:65], v[156:159], v[188:191], v[62:65]
	v_mfma_f32_16x16x32_bf16 v[62:65], v[160:163], v[192:195], v[62:65]
	v_mfma_f32_16x16x32_bf16 v[58:61], v[164:167], v[188:191], v[58:61]
	v_mfma_f32_16x16x32_bf16 v[58:61], v[168:171], v[192:195], v[58:61]
	v_mfma_f32_16x16x32_bf16 v[46:49], v[156:159], v[196:199], v[46:49]
	v_mfma_f32_16x16x32_bf16 v[46:49], v[160:163], v[200:203], v[46:49]
	v_mfma_f32_16x16x32_bf16 v[42:45], v[164:167], v[196:199], v[42:45]
	v_mfma_f32_16x16x32_bf16 v[42:45], v[168:171], v[200:203], v[42:45]
	v_mfma_f32_16x16x32_bf16 v[30:33], v[156:159], v[204:207], v[30:33]
	v_mfma_f32_16x16x32_bf16 v[30:33], v[160:163], v[208:211], v[30:33]
	v_mfma_f32_16x16x32_bf16 v[26:29], v[164:167], v[204:207], v[26:29]
	v_mfma_f32_16x16x32_bf16 v[26:29], v[168:171], v[208:211], v[26:29]
	v_mfma_f32_16x16x32_bf16 v[14:17], v[156:159], v[214:217], v[14:17]
	v_mfma_f32_16x16x32_bf16 v[14:17], v[160:163], v[218:221], v[14:17]
	v_mfma_f32_16x16x32_bf16 v[10:13], v[164:167], v[214:217], v[10:13]
	v_mfma_f32_16x16x32_bf16 v[10:13], v[168:171], v[218:221], v[10:13]
	v_mfma_f32_16x16x32_bf16 v[54:57], v[172:175], v[188:191], v[54:57]
	v_mfma_f32_16x16x32_bf16 v[54:57], v[176:179], v[192:195], v[54:57]
	v_mfma_f32_16x16x32_bf16 v[50:53], v[180:183], v[188:191], v[50:53]
	v_mfma_f32_16x16x32_bf16 v[50:53], v[184:187], v[192:195], v[50:53]
	v_mfma_f32_16x16x32_bf16 v[38:41], v[172:175], v[196:199], v[38:41]
	v_mfma_f32_16x16x32_bf16 v[38:41], v[176:179], v[200:203], v[38:41]
	v_mfma_f32_16x16x32_bf16 v[34:37], v[180:183], v[196:199], v[34:37]
	v_mfma_f32_16x16x32_bf16 v[34:37], v[184:187], v[200:203], v[34:37]
	v_mfma_f32_16x16x32_bf16 v[22:25], v[172:175], v[204:207], v[22:25]
	v_mfma_f32_16x16x32_bf16 v[22:25], v[176:179], v[208:211], v[22:25]
	v_mfma_f32_16x16x32_bf16 v[18:21], v[180:183], v[204:207], v[18:21]
	v_mfma_f32_16x16x32_bf16 v[18:21], v[184:187], v[208:211], v[18:21]
	v_mfma_f32_16x16x32_bf16 v[6:9], v[172:175], v[214:217], v[6:9]
	v_mfma_f32_16x16x32_bf16 v[6:9], v[176:179], v[218:221], v[6:9]
	v_mfma_f32_16x16x32_bf16 v[2:5], v[180:183], v[214:217], v[2:5]
	v_mfma_f32_16x16x32_bf16 v[2:5], v[184:187], v[218:221], v[2:5]
	s_barrier
	ds_read_b128 v[156:159], v153
	ds_read_b128 v[160:163], v153 offset:1024
	ds_read_b128 v[164:167], v153 offset:2048
	ds_read_b128 v[168:171], v153 offset:3072
	ds_read_b128 v[172:175], v154
	ds_read_b128 v[176:179], v154 offset:1024
	ds_read_b128 v[180:183], v154 offset:2048
	ds_read_b128 v[184:187], v154 offset:3072
	s_add_u32 s40, s40, 0x108000
	s_addc_u32 s41, s41, 0
	s_mov_b32 m0, s42
	v_lshl_add_u64 v[226:227], s[40:41], 0, v[130:131]
	ds_read_b128 v[188:191], v152 offset:32768
	ds_read_b128 v[192:195], v152 offset:33792
	ds_read_b128 v[196:199], v152 offset:34816
	ds_read_b128 v[200:203], v152 offset:35840
	ds_read_b128 v[204:207], v152 offset:36864
	ds_read_b128 v[208:211], v152 offset:37888
	ds_read_b128 v[214:217], v152 offset:38912
	ds_read_b128 v[218:221], v152 offset:39936
	global_load_lds_dwordx4 v[226:227], off
	v_lshl_add_u64 v[226:227], s[40:41], 0, v[134:135]
	s_mov_b32 m0, s43
	s_nop 0
	global_load_lds_dwordx4 v[226:227], off
	s_waitcnt vmcnt(8) lgkmcnt(0)
	s_barrier
	v_mfma_f32_16x16x32_bf16 v[126:129], v[156:159], v[188:191], v[126:129]
	v_mfma_f32_16x16x32_bf16 v[126:129], v[160:163], v[192:195], v[126:129]
	v_mfma_f32_16x16x32_bf16 v[122:125], v[164:167], v[188:191], v[122:125]
	v_mfma_f32_16x16x32_bf16 v[122:125], v[168:171], v[192:195], v[122:125]
	v_mfma_f32_16x16x32_bf16 v[110:113], v[156:159], v[196:199], v[110:113]
	v_mfma_f32_16x16x32_bf16 v[110:113], v[160:163], v[200:203], v[110:113]
	v_mfma_f32_16x16x32_bf16 v[106:109], v[164:167], v[196:199], v[106:109]
	v_mfma_f32_16x16x32_bf16 v[106:109], v[168:171], v[200:203], v[106:109]
	v_mfma_f32_16x16x32_bf16 v[94:97], v[156:159], v[204:207], v[94:97]
	v_mfma_f32_16x16x32_bf16 v[94:97], v[160:163], v[208:211], v[94:97]
	v_mfma_f32_16x16x32_bf16 v[90:93], v[164:167], v[204:207], v[90:93]
	v_mfma_f32_16x16x32_bf16 v[90:93], v[168:171], v[208:211], v[90:93]
	v_mfma_f32_16x16x32_bf16 v[78:81], v[156:159], v[214:217], v[78:81]
	v_mfma_f32_16x16x32_bf16 v[78:81], v[160:163], v[218:221], v[78:81]
	v_mfma_f32_16x16x32_bf16 v[74:77], v[164:167], v[214:217], v[74:77]
	v_mfma_f32_16x16x32_bf16 v[74:77], v[168:171], v[218:221], v[74:77]
	v_mfma_f32_16x16x32_bf16 v[118:121], v[172:175], v[188:191], v[118:121]
	v_mfma_f32_16x16x32_bf16 v[118:121], v[176:179], v[192:195], v[118:121]
	v_mfma_f32_16x16x32_bf16 v[114:117], v[180:183], v[188:191], v[114:117]
	v_mfma_f32_16x16x32_bf16 v[114:117], v[184:187], v[192:195], v[114:117]
	v_mfma_f32_16x16x32_bf16 v[102:105], v[172:175], v[196:199], v[102:105]
	v_mfma_f32_16x16x32_bf16 v[102:105], v[176:179], v[200:203], v[102:105]
	v_mfma_f32_16x16x32_bf16 v[98:101], v[180:183], v[196:199], v[98:101]
	v_mfma_f32_16x16x32_bf16 v[98:101], v[184:187], v[200:203], v[98:101]
	v_mfma_f32_16x16x32_bf16 v[86:89], v[172:175], v[204:207], v[86:89]
	v_mfma_f32_16x16x32_bf16 v[86:89], v[176:179], v[208:211], v[86:89]
	v_mfma_f32_16x16x32_bf16 v[82:85], v[180:183], v[204:207], v[82:85]
	v_mfma_f32_16x16x32_bf16 v[82:85], v[184:187], v[208:211], v[82:85]
	v_mfma_f32_16x16x32_bf16 v[70:73], v[172:175], v[214:217], v[70:73]
	v_mfma_f32_16x16x32_bf16 v[70:73], v[176:179], v[218:221], v[70:73]
	v_mfma_f32_16x16x32_bf16 v[66:69], v[180:183], v[214:217], v[66:69]
	v_mfma_f32_16x16x32_bf16 v[66:69], v[184:187], v[218:221], v[66:69]
	s_barrier
	s_mov_b32 m0, s53
	v_lshl_add_u64 v[222:223], v[222:223], 0, s[16:17]
	s_add_u32 s38, s38, 0x108080
	ds_read_b128 v[188:191], v152 offset:49152
	ds_read_b128 v[192:195], v152 offset:50176
	ds_read_b128 v[196:199], v152 offset:51200
	ds_read_b128 v[200:203], v152 offset:52224
	ds_read_b128 v[204:207], v152 offset:53248
	ds_read_b128 v[208:211], v152 offset:54272
	ds_read_b128 v[214:217], v152 offset:55296
	ds_read_b128 v[218:221], v152 offset:56320
	global_load_lds_dwordx4 v[222:223], off
	v_lshl_add_u64 v[222:223], v[224:225], 0, s[16:17]
	s_mov_b32 m0, s54
	s_addc_u32 s39, s39, 0
	s_add_i32 s40, s52, s2
	global_load_lds_dwordx4 v[222:223], off
	v_lshl_add_u64 v[222:223], s[38:39], 0, v[132:133]
	s_mov_b32 m0, s40
	s_nop 0
	global_load_lds_dwordx4 v[222:223], off
	v_lshl_add_u64 v[222:223], s[38:39], 0, v[136:137]
	s_add_i32 m0, s40, 0x2000
	s_nop 0
	global_load_lds_dwordx4 v[222:223], off
	v_lshl_add_u64 v[222:223], s[36:37], 0, v[130:131]
	s_mov_b32 m0, s44
	s_nop 0
	global_load_lds_dwordx4 v[222:223], off
	v_lshl_add_u64 v[222:223], s[36:37], 0, v[134:135]
	s_mov_b32 m0, s45
	s_nop 0
	global_load_lds_dwordx4 v[222:223], off
	s_waitcnt vmcnt(8) lgkmcnt(0)
	s_barrier
	v_mfma_f32_16x16x32_bf16 v[62:65], v[156:159], v[188:191], v[62:65]
	v_mfma_f32_16x16x32_bf16 v[62:65], v[160:163], v[192:195], v[62:65]
	v_mfma_f32_16x16x32_bf16 v[58:61], v[164:167], v[188:191], v[58:61]
	v_mfma_f32_16x16x32_bf16 v[58:61], v[168:171], v[192:195], v[58:61]
	v_mfma_f32_16x16x32_bf16 v[46:49], v[156:159], v[196:199], v[46:49]
	v_mfma_f32_16x16x32_bf16 v[46:49], v[160:163], v[200:203], v[46:49]
	v_mfma_f32_16x16x32_bf16 v[42:45], v[164:167], v[196:199], v[42:45]
	v_mfma_f32_16x16x32_bf16 v[42:45], v[168:171], v[200:203], v[42:45]
	v_mfma_f32_16x16x32_bf16 v[30:33], v[156:159], v[204:207], v[30:33]
	v_mfma_f32_16x16x32_bf16 v[30:33], v[160:163], v[208:211], v[30:33]
	v_mfma_f32_16x16x32_bf16 v[26:29], v[164:167], v[204:207], v[26:29]
	v_mfma_f32_16x16x32_bf16 v[26:29], v[168:171], v[208:211], v[26:29]
	v_mfma_f32_16x16x32_bf16 v[14:17], v[156:159], v[214:217], v[14:17]
	v_mfma_f32_16x16x32_bf16 v[14:17], v[160:163], v[218:221], v[14:17]
	v_mfma_f32_16x16x32_bf16 v[10:13], v[164:167], v[214:217], v[10:13]
	v_mfma_f32_16x16x32_bf16 v[10:13], v[168:171], v[218:221], v[10:13]
	v_mfma_f32_16x16x32_bf16 v[54:57], v[172:175], v[188:191], v[54:57]
	v_mfma_f32_16x16x32_bf16 v[54:57], v[176:179], v[192:195], v[54:57]
	v_mfma_f32_16x16x32_bf16 v[50:53], v[180:183], v[188:191], v[50:53]
	v_mfma_f32_16x16x32_bf16 v[50:53], v[184:187], v[192:195], v[50:53]
	v_mfma_f32_16x16x32_bf16 v[38:41], v[172:175], v[196:199], v[38:41]
	v_mfma_f32_16x16x32_bf16 v[38:41], v[176:179], v[200:203], v[38:41]
	v_mfma_f32_16x16x32_bf16 v[34:37], v[180:183], v[196:199], v[34:37]
	v_mfma_f32_16x16x32_bf16 v[34:37], v[184:187], v[200:203], v[34:37]
	v_mfma_f32_16x16x32_bf16 v[22:25], v[172:175], v[204:207], v[22:25]
	v_mfma_f32_16x16x32_bf16 v[22:25], v[176:179], v[208:211], v[22:25]
	v_mfma_f32_16x16x32_bf16 v[18:21], v[180:183], v[204:207], v[18:21]
	v_mfma_f32_16x16x32_bf16 v[18:21], v[184:187], v[208:211], v[18:21]
	v_mfma_f32_16x16x32_bf16 v[6:9], v[172:175], v[214:217], v[6:9]
	v_mfma_f32_16x16x32_bf16 v[6:9], v[176:179], v[218:221], v[6:9]
	v_mfma_f32_16x16x32_bf16 v[2:5], v[180:183], v[214:217], v[2:5]
	v_mfma_f32_16x16x32_bf16 v[2:5], v[184:187], v[218:221], v[2:5]
	s_barrier
	s_add_i32 s64, s64, 2
	s_add_u32 s34, s34, 0x100
	s_addc_u32 s35, s35, 0
	s_cmp_gt_u32 s64, 61
	s_cbranch_scc0 .LBB0_235
	s_and_b64 vcc, exec, s[20:21]
	s_cbranch_vccz .LBB0_238
	s_barrier

.LBB0_434:
	ds_read_b128 v[134:137], v204
	ds_read_b128 v[138:141], v204 offset:1024
	ds_read_b128 v[142:145], v204 offset:2048
	ds_read_b128 v[146:149], v204 offset:3072
	ds_read_b128 v[150:153], v205
	ds_read_b128 v[154:157], v205 offset:1024
	ds_read_b128 v[158:161], v205 offset:2048
	ds_read_b128 v[162:165], v205 offset:3072
	s_add_u32 s34, s22, s30
	s_addc_u32 s35, s23, s31
	s_add_u32 s38, s34, 0x100
	s_addc_u32 s39, s35, 0
	s_add_u32 s36, s60, s30
	s_addc_u32 s37, s61, s31
	s_add_u32 s34, s34, 0x180
	s_addc_u32 s35, s35, 0
	s_cmpk_eq_i32 s30, 0xb00
	s_cselect_b32 s35, s59, s35
	s_cselect_b32 s34, s58, s34
	s_cselect_b32 s37, s21, s37
	s_cselect_b32 s36, s20, s36
	s_cselect_b32 s39, s17, s39
	s_cselect_b32 s38, s16, s38
	v_lshl_add_u64 v[200:201], v[130:131], 0, s[30:31]
	s_add_i32 m0, s3, 0xc000
	ds_read_b128 v[166:169], v206
	ds_read_b128 v[170:173], v206 offset:1024
	ds_read_b128 v[174:177], v206 offset:2048
	ds_read_b128 v[178:181], v206 offset:3072
	ds_read_b128 v[182:185], v206 offset:4096
	ds_read_b128 v[208:211], v206 offset:5120
	ds_read_b128 v[214:217], v206 offset:6144
	ds_read_b128 v[218:221], v206 offset:7168
	global_load_lds_dwordx4 v[200:201], off
	v_lshl_add_u64 v[200:201], v[132:133], 0, s[30:31]
	s_add_i32 m0, s3, 0xe000
	s_nop 0
	global_load_lds_dwordx4 v[200:201], off
	s_waitcnt vmcnt(8) lgkmcnt(0)
	s_barrier
	v_mfma_f32_16x16x32_bf16 v[126:129], v[134:137], v[166:169], v[126:129]
	v_mfma_f32_16x16x32_bf16 v[126:129], v[138:141], v[170:173], v[126:129]
	v_mfma_f32_16x16x32_bf16 v[122:125], v[142:145], v[166:169], v[122:125]
	v_mfma_f32_16x16x32_bf16 v[122:125], v[146:149], v[170:173], v[122:125]
	v_mfma_f32_16x16x32_bf16 v[110:113], v[134:137], v[174:177], v[110:113]
	v_mfma_f32_16x16x32_bf16 v[110:113], v[138:141], v[178:181], v[110:113]
	v_mfma_f32_16x16x32_bf16 v[106:109], v[142:145], v[174:177], v[106:109]
	v_mfma_f32_16x16x32_bf16 v[106:109], v[146:149], v[178:181], v[106:109]
	v_mfma_f32_16x16x32_bf16 v[94:97], v[134:137], v[182:185], v[94:97]
	v_mfma_f32_16x16x32_bf16 v[94:97], v[138:141], v[208:211], v[94:97]
	v_mfma_f32_16x16x32_bf16 v[90:93], v[142:145], v[182:185], v[90:93]
	v_mfma_f32_16x16x32_bf16 v[90:93], v[146:149], v[208:211], v[90:93]
	v_mfma_f32_16x16x32_bf16 v[78:81], v[134:137], v[214:217], v[78:81]
	v_mfma_f32_16x16x32_bf16 v[78:81], v[138:141], v[218:221], v[78:81]
	v_mfma_f32_16x16x32_bf16 v[74:77], v[142:145], v[214:217], v[74:77]
	v_mfma_f32_16x16x32_bf16 v[74:77], v[146:149], v[218:221], v[74:77]
	v_mfma_f32_16x16x32_bf16 v[118:121], v[150:153], v[166:169], v[118:121]
	v_mfma_f32_16x16x32_bf16 v[118:121], v[154:157], v[170:173], v[118:121]
	v_mfma_f32_16x16x32_bf16 v[114:117], v[158:161], v[166:169], v[114:117]
	v_mfma_f32_16x16x32_bf16 v[114:117], v[162:165], v[170:173], v[114:117]
	v_mfma_f32_16x16x32_bf16 v[102:105], v[150:153], v[174:177], v[102:105]
	v_mfma_f32_16x16x32_bf16 v[102:105], v[154:157], v[178:181], v[102:105]
	v_mfma_f32_16x16x32_bf16 v[98:101], v[158:161], v[174:177], v[98:101]
	v_mfma_f32_16x16x32_bf16 v[98:101], v[162:165], v[178:181], v[98:101]
	v_mfma_f32_16x16x32_bf16 v[86:89], v[150:153], v[182:185], v[86:89]
	v_mfma_f32_16x16x32_bf16 v[86:89], v[154:157], v[208:211], v[86:89]
	v_mfma_f32_16x16x32_bf16 v[82:85], v[158:161], v[182:185], v[82:85]
	v_mfma_f32_16x16x32_bf16 v[82:85], v[162:165], v[208:211], v[82:85]
	v_mfma_f32_16x16x32_bf16 v[70:73], v[150:153], v[214:217], v[70:73]
	v_mfma_f32_16x16x32_bf16 v[70:73], v[154:157], v[218:221], v[70:73]
	v_mfma_f32_16x16x32_bf16 v[66:69], v[158:161], v[214:217], v[66:69]
	v_mfma_f32_16x16x32_bf16 v[66:69], v[162:165], v[218:221], v[66:69]
	s_barrier
	s_add_i32 s63, s52, s2
	v_lshl_add_u64 v[200:201], s[36:37], 0, v[188:189]
	s_mov_b32 m0, s63
	ds_read_b128 v[166:169], v206 offset:16384
	ds_read_b128 v[170:173], v206 offset:17408
	ds_read_b128 v[174:177], v206 offset:18432
	ds_read_b128 v[178:181], v206 offset:19456
	ds_read_b128 v[182:185], v206 offset:20480
	ds_read_b128 v[208:211], v206 offset:21504
	ds_read_b128 v[214:217], v206 offset:22528
	ds_read_b128 v[218:221], v206 offset:23552
	global_load_lds_dwordx4 v[200:201], off
	s_add_i32 m0, s63, 0x2000
	s_add_u32 s64, s36, 0x68000
	v_lshl_add_u64 v[222:223], s[36:37], 0, v[192:193]
	s_addc_u32 s65, s37, 0
	s_add_i32 s63, s53, s2
	global_load_lds_dwordx4 v[222:223], off
	v_lshl_add_u64 v[224:225], s[64:65], 0, v[188:189]
	s_mov_b32 m0, s63
	s_nop 0
	global_load_lds_dwordx4 v[224:225], off
	v_lshl_add_u64 v[224:225], s[64:65], 0, v[192:193]
	s_add_i32 m0, s63, 0x2000
	s_nop 0
	global_load_lds_dwordx4 v[224:225], off
	v_lshl_add_u64 v[224:225], s[38:39], 0, v[186:187]
	s_mov_b32 m0, s3
	s_nop 0
	global_load_lds_dwordx4 v[224:225], off
	v_lshl_add_u64 v[224:225], s[38:39], 0, v[190:191]
	s_mov_b32 m0, s33
	s_nop 0
	global_load_lds_dwordx4 v[224:225], off
	s_waitcnt vmcnt(8) lgkmcnt(0)
	s_barrier
	v_mfma_f32_16x16x32_bf16 v[62:65], v[134:137], v[166:169], v[62:65]
	v_mfma_f32_16x16x32_bf16 v[62:65], v[138:141], v[170:173], v[62:65]
	v_mfma_f32_16x16x32_bf16 v[58:61], v[142:145], v[166:169], v[58:61]
	v_mfma_f32_16x16x32_bf16 v[58:61], v[146:149], v[170:173], v[58:61]
	v_mfma_f32_16x16x32_bf16 v[46:49], v[134:137], v[174:177], v[46:49]
	v_mfma_f32_16x16x32_bf16 v[46:49], v[138:141], v[178:181], v[46:49]
	v_mfma_f32_16x16x32_bf16 v[42:45], v[142:145], v[174:177], v[42:45]
	v_mfma_f32_16x16x32_bf16 v[42:45], v[146:149], v[178:181], v[42:45]
	v_mfma_f32_16x16x32_bf16 v[30:33], v[134:137], v[182:185], v[30:33]
	v_mfma_f32_16x16x32_bf16 v[30:33], v[138:141], v[208:211], v[30:33]
	v_mfma_f32_16x16x32_bf16 v[26:29], v[142:145], v[182:185], v[26:29]
	v_mfma_f32_16x16x32_bf16 v[26:29], v[146:149], v[208:211], v[26:29]
	v_mfma_f32_16x16x32_bf16 v[14:17], v[134:137], v[214:217], v[14:17]
	v_mfma_f32_16x16x32_bf16 v[14:17], v[138:141], v[218:221], v[14:17]
	v_mfma_f32_16x16x32_bf16 v[10:13], v[142:145], v[214:217], v[10:13]
	v_mfma_f32_16x16x32_bf16 v[10:13], v[146:149], v[218:221], v[10:13]
	v_mfma_f32_16x16x32_bf16 v[54:57], v[150:153], v[166:169], v[54:57]
	v_mfma_f32_16x16x32_bf16 v[54:57], v[154:157], v[170:173], v[54:57]
	v_mfma_f32_16x16x32_bf16 v[50:53], v[158:161], v[166:169], v[50:53]
	v_mfma_f32_16x16x32_bf16 v[50:53], v[162:165], v[170:173], v[50:53]
	v_mfma_f32_16x16x32_bf16 v[38:41], v[150:153], v[174:177], v[38:41]
	v_mfma_f32_16x16x32_bf16 v[38:41], v[154:157], v[178:181], v[38:41]
	v_mfma_f32_16x16x32_bf16 v[34:37], v[158:161], v[174:177], v[34:37]
	v_mfma_f32_16x16x32_bf16 v[34:37], v[162:165], v[178:181], v[34:37]
	v_mfma_f32_16x16x32_bf16 v[22:25], v[150:153], v[182:185], v[22:25]
	v_mfma_f32_16x16x32_bf16 v[22:25], v[154:157], v[208:211], v[22:25]
	v_mfma_f32_16x16x32_bf16 v[18:21], v[158:161], v[182:185], v[18:21]
	v_mfma_f32_16x16x32_bf16 v[18:21], v[162:165], v[208:211], v[18:21]
	v_mfma_f32_16x16x32_bf16 v[6:9], v[150:153], v[214:217], v[6:9]
	v_mfma_f32_16x16x32_bf16 v[6:9], v[154:157], v[218:221], v[6:9]
	v_mfma_f32_16x16x32_bf16 v[2:5], v[158:161], v[214:217], v[2:5]
	v_mfma_f32_16x16x32_bf16 v[2:5], v[162:165], v[218:221], v[2:5]
	s_barrier
	s_add_i32 s63, 0, 0x18000
	s_add_i32 s64, 0, 0x1c000
	v_add_u32_e32 v146, s63, v202
	v_add_u32_e32 v162, s64, v202
	ds_read_b128 v[134:137], v146
	ds_read_b128 v[138:141], v146 offset:1024
	ds_read_b128 v[142:145], v146 offset:2048
	ds_read_b128 v[146:149], v146 offset:3072
	ds_read_b128 v[150:153], v162
	ds_read_b128 v[154:157], v162 offset:1024
	ds_read_b128 v[158:161], v162 offset:2048
	ds_read_b128 v[162:165], v162 offset:3072
	s_add_u32 s38, s38, 0x188000
	s_addc_u32 s39, s39, 0
	s_mov_b32 m0, s40
	v_lshl_add_u64 v[224:225], s[38:39], 0, v[186:187]
	ds_read_b128 v[166:169], v206 offset:32768
	ds_read_b128 v[170:173], v206 offset:33792
	ds_read_b128 v[174:177], v206 offset:34816
	ds_read_b128 v[178:181], v206 offset:35840
	ds_read_b128 v[182:185], v206 offset:36864
	ds_read_b128 v[208:211], v206 offset:37888
	ds_read_b128 v[214:217], v206 offset:38912
	ds_read_b128 v[218:221], v206 offset:39936
	global_load_lds_dwordx4 v[224:225], off
	v_lshl_add_u64 v[224:225], s[38:39], 0, v[190:191]
	s_mov_b32 m0, s41
	s_nop 0
	global_load_lds_dwordx4 v[224:225], off
	s_waitcnt vmcnt(8) lgkmcnt(0)
	s_barrier
	v_mfma_f32_16x16x32_bf16 v[126:129], v[134:137], v[166:169], v[126:129]
	v_mfma_f32_16x16x32_bf16 v[126:129], v[138:141], v[170:173], v[126:129]
	v_mfma_f32_16x16x32_bf16 v[122:125], v[142:145], v[166:169], v[122:125]
	v_mfma_f32_16x16x32_bf16 v[122:125], v[146:149], v[170:173], v[122:125]
	v_mfma_f32_16x16x32_bf16 v[110:113], v[134:137], v[174:177], v[110:113]
	v_mfma_f32_16x16x32_bf16 v[110:113], v[138:141], v[178:181], v[110:113]
	v_mfma_f32_16x16x32_bf16 v[106:109], v[142:145], v[174:177], v[106:109]
	v_mfma_f32_16x16x32_bf16 v[106:109], v[146:149], v[178:181], v[106:109]
	v_mfma_f32_16x16x32_bf16 v[94:97], v[134:137], v[182:185], v[94:97]
	v_mfma_f32_16x16x32_bf16 v[94:97], v[138:141], v[208:211], v[94:97]
	v_mfma_f32_16x16x32_bf16 v[90:93], v[142:145], v[182:185], v[90:93]
	v_mfma_f32_16x16x32_bf16 v[90:93], v[146:149], v[208:211], v[90:93]
	v_mfma_f32_16x16x32_bf16 v[78:81], v[134:137], v[214:217], v[78:81]
	v_mfma_f32_16x16x32_bf16 v[78:81], v[138:141], v[218:221], v[78:81]
	v_mfma_f32_16x16x32_bf16 v[74:77], v[142:145], v[214:217], v[74:77]
	v_mfma_f32_16x16x32_bf16 v[74:77], v[146:149], v[218:221], v[74:77]
	v_mfma_f32_16x16x32_bf16 v[118:121], v[150:153], v[166:169], v[118:121]
	v_mfma_f32_16x16x32_bf16 v[118:121], v[154:157], v[170:173], v[118:121]
	v_mfma_f32_16x16x32_bf16 v[114:117], v[158:161], v[166:169], v[114:117]
	v_mfma_f32_16x16x32_bf16 v[114:117], v[162:165], v[170:173], v[114:117]
	v_mfma_f32_16x16x32_bf16 v[102:105], v[150:153], v[174:177], v[102:105]
	v_mfma_f32_16x16x32_bf16 v[102:105], v[154:157], v[178:181], v[102:105]
	v_mfma_f32_16x16x32_bf16 v[98:101], v[158:161], v[174:177], v[98:101]
	v_mfma_f32_16x16x32_bf16 v[98:101], v[162:165], v[178:181], v[98:101]
	v_mfma_f32_16x16x32_bf16 v[86:89], v[150:153], v[182:185], v[86:89]
	v_mfma_f32_16x16x32_bf16 v[86:89], v[154:157], v[208:211], v[86:89]
	v_mfma_f32_16x16x32_bf16 v[82:85], v[158:161], v[182:185], v[82:85]
	v_mfma_f32_16x16x32_bf16 v[82:85], v[162:165], v[208:211], v[82:85]
	v_mfma_f32_16x16x32_bf16 v[70:73], v[150:153], v[214:217], v[70:73]
	v_mfma_f32_16x16x32_bf16 v[70:73], v[154:157], v[218:221], v[70:73]
	v_mfma_f32_16x16x32_bf16 v[66:69], v[158:161], v[214:217], v[66:69]
	v_mfma_f32_16x16x32_bf16 v[66:69], v[162:165], v[218:221], v[66:69]
	s_barrier
	s_add_i32 s38, s63, s2
	v_lshl_add_u64 v[200:201], v[200:201], 0, s[12:13]
	s_mov_b32 m0, s38
	ds_read_b128 v[166:169], v206 offset:49152
	ds_read_b128 v[170:173], v206 offset:50176
	ds_read_b128 v[174:177], v206 offset:51200
	ds_read_b128 v[178:181], v206 offset:52224
	ds_read_b128 v[182:185], v206 offset:53248
	ds_read_b128 v[208:211], v206 offset:54272
	ds_read_b128 v[214:217], v206 offset:55296
	ds_read_b128 v[218:221], v206 offset:56320
	global_load_lds_dwordx4 v[200:201], off
	s_add_i32 m0, s38, 0x2000
	s_add_u32 s36, s36, 0x68080
	v_lshl_add_u64 v[200:201], v[222:223], 0, s[12:13]
	s_addc_u32 s37, s37, 0
	s_add_i32 s38, s64, s2
	global_load_lds_dwordx4 v[200:201], off
	v_lshl_add_u64 v[200:201], s[36:37], 0, v[188:189]
	s_mov_b32 m0, s38
	s_nop 0
	global_load_lds_dwordx4 v[200:201], off
	v_lshl_add_u64 v[200:201], s[36:37], 0, v[192:193]
	s_add_i32 m0, s38, 0x2000
	s_nop 0
	global_load_lds_dwordx4 v[200:201], off
	v_lshl_add_u64 v[200:201], s[34:35], 0, v[186:187]
	s_mov_b32 m0, s50
	s_nop 0
	global_load_lds_dwordx4 v[200:201], off
	v_lshl_add_u64 v[200:201], s[34:35], 0, v[190:191]
	s_mov_b32 m0, s51
	s_nop 0
	global_load_lds_dwordx4 v[200:201], off
	s_waitcnt vmcnt(8) lgkmcnt(0)
	s_barrier
	v_mfma_f32_16x16x32_bf16 v[62:65], v[134:137], v[166:169], v[62:65]
	v_mfma_f32_16x16x32_bf16 v[62:65], v[138:141], v[170:173], v[62:65]
	v_mfma_f32_16x16x32_bf16 v[58:61], v[142:145], v[166:169], v[58:61]
	v_mfma_f32_16x16x32_bf16 v[58:61], v[146:149], v[170:173], v[58:61]
	v_mfma_f32_16x16x32_bf16 v[46:49], v[134:137], v[174:177], v[46:49]
	v_mfma_f32_16x16x32_bf16 v[46:49], v[138:141], v[178:181], v[46:49]
	v_mfma_f32_16x16x32_bf16 v[42:45], v[142:145], v[174:177], v[42:45]
	v_mfma_f32_16x16x32_bf16 v[42:45], v[146:149], v[178:181], v[42:45]
	v_mfma_f32_16x16x32_bf16 v[30:33], v[134:137], v[182:185], v[30:33]
	v_mfma_f32_16x16x32_bf16 v[30:33], v[138:141], v[208:211], v[30:33]
	v_mfma_f32_16x16x32_bf16 v[26:29], v[142:145], v[182:185], v[26:29]
	v_mfma_f32_16x16x32_bf16 v[26:29], v[146:149], v[208:211], v[26:29]
	v_mfma_f32_16x16x32_bf16 v[14:17], v[134:137], v[214:217], v[14:17]
	v_mfma_f32_16x16x32_bf16 v[14:17], v[138:141], v[218:221], v[14:17]
	v_mfma_f32_16x16x32_bf16 v[10:13], v[142:145], v[214:217], v[10:13]
	v_mfma_f32_16x16x32_bf16 v[10:13], v[146:149], v[218:221], v[10:13]
	v_mfma_f32_16x16x32_bf16 v[54:57], v[150:153], v[166:169], v[54:57]
	v_mfma_f32_16x16x32_bf16 v[54:57], v[154:157], v[170:173], v[54:57]
	v_mfma_f32_16x16x32_bf16 v[50:53], v[158:161], v[166:169], v[50:53]
	v_mfma_f32_16x16x32_bf16 v[50:53], v[162:165], v[170:173], v[50:53]
	v_mfma_f32_16x16x32_bf16 v[38:41], v[150:153], v[174:177], v[38:41]
	v_mfma_f32_16x16x32_bf16 v[38:41], v[154:157], v[178:181], v[38:41]
	v_mfma_f32_16x16x32_bf16 v[34:37], v[158:161], v[174:177], v[34:37]
	v_mfma_f32_16x16x32_bf16 v[34:37], v[162:165], v[178:181], v[34:37]
	v_mfma_f32_16x16x32_bf16 v[22:25], v[150:153], v[182:185], v[22:25]
	v_mfma_f32_16x16x32_bf16 v[22:25], v[154:157], v[208:211], v[22:25]
	v_mfma_f32_16x16x32_bf16 v[18:21], v[158:161], v[182:185], v[18:21]
	v_mfma_f32_16x16x32_bf16 v[18:21], v[162:165], v[208:211], v[18:21]
	v_mfma_f32_16x16x32_bf16 v[6:9], v[150:153], v[214:217], v[6:9]
	v_mfma_f32_16x16x32_bf16 v[6:9], v[154:157], v[218:221], v[6:9]
	v_mfma_f32_16x16x32_bf16 v[2:5], v[158:161], v[214:217], v[2:5]
	v_mfma_f32_16x16x32_bf16 v[2:5], v[162:165], v[218:221], v[2:5]
	s_barrier
	s_add_i32 s62, s62, 2
	s_add_u32 s30, s30, 0x100
	s_addc_u32 s31, s31, 0
	s_cmp_gt_u32 s62, 21
	s_cbranch_scc0 .LBB0_434
	s_and_b64 vcc, exec, s[14:15]
	s_cbranch_vccz .LBB0_437
	s_barrier

.LBB0_519:
	s_add_i32 s39, s56, 0xfffe8000
	s_and_b32 s38, s36, 0x100
	s_and_b32 s39, s39, 0x3e0000
	s_or_b32 s38, s38, s39
	s_add_u32 s57, s34, s38
	s_addc_u32 s59, s35, 0
	s_add_u32 s38, s36, 0x100
	s_addc_u32 s39, s37, 0
	s_add_i32 s41, s56, 0xffff8000
	s_and_b32 s40, s38, 0x100
	s_and_b32 s41, s41, 0x7e0000
	s_or_b32 s40, s41, s40
	s_add_u32 s40, s34, s40
	s_addc_u32 s41, s35, 0
	s_add_u32 s58, s53, s36
	s_addc_u32 s37, s54, s37
	s_add_i32 s42, s36, 0x180
	s_and_b32 s42, s42, 0x180
	s_and_b32 s43, s56, 0x7e0000
	s_or_b32 s42, s43, s42
	s_add_u32 s60, s34, s42
	s_addc_u32 s61, s35, 0
	s_cmpk_eq_i32 s36, 0x3f00
	s_cselect_b32 s43, s1, s41
	s_cselect_b32 s42, s21, s40
	s_cselect_b32 s41, s23, s37
	s_cselect_b32 s40, s22, s58
	s_cselect_b32 s37, s52, s61
	s_cselect_b32 s36, s31, s60
	s_add_i32 s60, 0, 0x10000
	v_add_u32_e32 v1, s60, v199
	ds_read_b128 v[130:133], v1
	ds_read_b128 v[134:137], v1 offset:1024
	ds_read_b128 v[138:141], v1 offset:2048
	ds_read_b128 v[142:145], v1 offset:3072
	ds_read_b128 v[146:149], v201
	ds_read_b128 v[150:153], v201 offset:1024
	ds_read_b128 v[154:157], v201 offset:2048
	ds_read_b128 v[158:161], v201 offset:3072
	s_add_u32 s58, s57, 0x10080
	s_addc_u32 s59, s59, 0
	v_lshl_add_u64 v[208:209], s[58:59], 0, v[178:179]
	s_add_i32 m0, s3, 0xc000
	ds_read_b128 v[162:165], v202
	ds_read_b128 v[166:169], v202 offset:1024
	ds_read_b128 v[170:173], v202 offset:2048
	ds_read_b128 v[174:177], v202 offset:3072
	ds_read_b128 v[186:189], v202 offset:4096
	ds_read_b128 v[190:193], v202 offset:5120
	ds_read_b128 v[194:197], v202 offset:6144
	ds_read_b128 v[204:207], v202 offset:7168
	global_load_lds_dwordx4 v[208:209], off
	v_lshl_add_u64 v[208:209], s[58:59], 0, v[182:183]
	s_add_i32 m0, s3, 0xe000
	s_nop 0
	global_load_lds_dwordx4 v[208:209], off
	s_waitcnt vmcnt(8) lgkmcnt(0)
	s_barrier
	v_mfma_f32_16x16x32_bf16 v[126:129], v[130:133], v[162:165], v[126:129]
	v_mfma_f32_16x16x32_bf16 v[126:129], v[134:137], v[166:169], v[126:129]
	v_mfma_f32_16x16x32_bf16 v[122:125], v[138:141], v[162:165], v[122:125]
	v_mfma_f32_16x16x32_bf16 v[122:125], v[142:145], v[166:169], v[122:125]
	v_mfma_f32_16x16x32_bf16 v[110:113], v[130:133], v[170:173], v[110:113]
	v_mfma_f32_16x16x32_bf16 v[110:113], v[134:137], v[174:177], v[110:113]
	v_mfma_f32_16x16x32_bf16 v[106:109], v[138:141], v[170:173], v[106:109]
	v_mfma_f32_16x16x32_bf16 v[106:109], v[142:145], v[174:177], v[106:109]
	v_mfma_f32_16x16x32_bf16 v[94:97], v[130:133], v[186:189], v[94:97]
	v_mfma_f32_16x16x32_bf16 v[94:97], v[134:137], v[190:193], v[94:97]
	v_mfma_f32_16x16x32_bf16 v[90:93], v[138:141], v[186:189], v[90:93]
	v_mfma_f32_16x16x32_bf16 v[90:93], v[142:145], v[190:193], v[90:93]
	v_mfma_f32_16x16x32_bf16 v[78:81], v[130:133], v[194:197], v[78:81]
	v_mfma_f32_16x16x32_bf16 v[78:81], v[134:137], v[204:207], v[78:81]
	v_mfma_f32_16x16x32_bf16 v[74:77], v[138:141], v[194:197], v[74:77]
	v_mfma_f32_16x16x32_bf16 v[74:77], v[142:145], v[204:207], v[74:77]
	v_mfma_f32_16x16x32_bf16 v[118:121], v[146:149], v[162:165], v[118:121]
	v_mfma_f32_16x16x32_bf16 v[118:121], v[150:153], v[166:169], v[118:121]
	v_mfma_f32_16x16x32_bf16 v[114:117], v[154:157], v[162:165], v[114:117]
	v_mfma_f32_16x16x32_bf16 v[114:117], v[158:161], v[166:169], v[114:117]
	v_mfma_f32_16x16x32_bf16 v[102:105], v[146:149], v[170:173], v[102:105]
	v_mfma_f32_16x16x32_bf16 v[102:105], v[150:153], v[174:177], v[102:105]
	v_mfma_f32_16x16x32_bf16 v[98:101], v[154:157], v[170:173], v[98:101]
	v_mfma_f32_16x16x32_bf16 v[98:101], v[158:161], v[174:177], v[98:101]
	v_mfma_f32_16x16x32_bf16 v[86:89], v[146:149], v[186:189], v[86:89]
	v_mfma_f32_16x16x32_bf16 v[86:89], v[150:153], v[190:193], v[86:89]
	v_mfma_f32_16x16x32_bf16 v[82:85], v[154:157], v[186:189], v[82:85]
	v_mfma_f32_16x16x32_bf16 v[82:85], v[158:161], v[190:193], v[82:85]
	v_mfma_f32_16x16x32_bf16 v[70:73], v[146:149], v[194:197], v[70:73]
	v_mfma_f32_16x16x32_bf16 v[70:73], v[150:153], v[204:207], v[70:73]
	v_mfma_f32_16x16x32_bf16 v[66:69], v[154:157], v[194:197], v[66:69]
	v_mfma_f32_16x16x32_bf16 v[66:69], v[158:161], v[204:207], v[66:69]
	s_barrier
	s_add_i32 s57, s60, s2
	v_lshl_add_u64 v[208:209], s[40:41], 0, v[180:181]
	s_mov_b32 m0, s57
	ds_read_b128 v[162:165], v202 offset:16384
	ds_read_b128 v[166:169], v202 offset:17408
	ds_read_b128 v[170:173], v202 offset:18432
	ds_read_b128 v[174:177], v202 offset:19456
	ds_read_b128 v[186:189], v202 offset:20480
	ds_read_b128 v[190:193], v202 offset:21504
	ds_read_b128 v[194:197], v202 offset:22528
	ds_read_b128 v[204:207], v202 offset:23552
	global_load_lds_dwordx4 v[208:209], off
	s_add_i32 m0, s57, 0x2000
	s_add_u32 s58, s40, 0x208000
	v_lshl_add_u64 v[210:211], s[40:41], 0, v[184:185]
	s_addc_u32 s59, s41, 0
	s_add_i32 s57, s49, s2
	global_load_lds_dwordx4 v[210:211], off
	v_lshl_add_u64 v[214:215], s[58:59], 0, v[180:181]
	s_mov_b32 m0, s57
	s_nop 0
	global_load_lds_dwordx4 v[214:215], off
	v_lshl_add_u64 v[214:215], s[58:59], 0, v[184:185]
	s_add_i32 m0, s57, 0x2000
	s_nop 0
	global_load_lds_dwordx4 v[214:215], off
	v_lshl_add_u64 v[214:215], s[42:43], 0, v[178:179]
	s_mov_b32 m0, s3
	s_nop 0
	global_load_lds_dwordx4 v[214:215], off
	v_lshl_add_u64 v[214:215], s[42:43], 0, v[182:183]
	s_mov_b32 m0, s33
	s_nop 0
	global_load_lds_dwordx4 v[214:215], off
	s_waitcnt vmcnt(8) lgkmcnt(0)
	s_barrier
	v_mfma_f32_16x16x32_bf16 v[62:65], v[130:133], v[162:165], v[62:65]
	v_mfma_f32_16x16x32_bf16 v[62:65], v[134:137], v[166:169], v[62:65]
	v_mfma_f32_16x16x32_bf16 v[58:61], v[138:141], v[162:165], v[58:61]
	v_mfma_f32_16x16x32_bf16 v[58:61], v[142:145], v[166:169], v[58:61]
	v_mfma_f32_16x16x32_bf16 v[46:49], v[130:133], v[170:173], v[46:49]
	v_mfma_f32_16x16x32_bf16 v[46:49], v[134:137], v[174:177], v[46:49]
	v_mfma_f32_16x16x32_bf16 v[42:45], v[138:141], v[170:173], v[42:45]
	v_mfma_f32_16x16x32_bf16 v[42:45], v[142:145], v[174:177], v[42:45]
	v_mfma_f32_16x16x32_bf16 v[30:33], v[130:133], v[186:189], v[30:33]
	v_mfma_f32_16x16x32_bf16 v[30:33], v[134:137], v[190:193], v[30:33]
	v_mfma_f32_16x16x32_bf16 v[26:29], v[138:141], v[186:189], v[26:29]
	v_mfma_f32_16x16x32_bf16 v[26:29], v[142:145], v[190:193], v[26:29]
	v_mfma_f32_16x16x32_bf16 v[14:17], v[130:133], v[194:197], v[14:17]
	v_mfma_f32_16x16x32_bf16 v[14:17], v[134:137], v[204:207], v[14:17]
	v_mfma_f32_16x16x32_bf16 v[10:13], v[138:141], v[194:197], v[10:13]
	v_mfma_f32_16x16x32_bf16 v[10:13], v[142:145], v[204:207], v[10:13]
	v_mfma_f32_16x16x32_bf16 v[54:57], v[146:149], v[162:165], v[54:57]
	v_mfma_f32_16x16x32_bf16 v[54:57], v[150:153], v[166:169], v[54:57]
	v_mfma_f32_16x16x32_bf16 v[50:53], v[154:157], v[162:165], v[50:53]
	v_mfma_f32_16x16x32_bf16 v[50:53], v[158:161], v[166:169], v[50:53]
	v_mfma_f32_16x16x32_bf16 v[38:41], v[146:149], v[170:173], v[38:41]
	v_mfma_f32_16x16x32_bf16 v[38:41], v[150:153], v[174:177], v[38:41]
	v_mfma_f32_16x16x32_bf16 v[34:37], v[154:157], v[170:173], v[34:37]
	v_mfma_f32_16x16x32_bf16 v[34:37], v[158:161], v[174:177], v[34:37]
	v_mfma_f32_16x16x32_bf16 v[22:25], v[146:149], v[186:189], v[22:25]
	v_mfma_f32_16x16x32_bf16 v[22:25], v[150:153], v[190:193], v[22:25]
	v_mfma_f32_16x16x32_bf16 v[18:21], v[154:157], v[186:189], v[18:21]
	v_mfma_f32_16x16x32_bf16 v[18:21], v[158:161], v[190:193], v[18:21]
	v_mfma_f32_16x16x32_bf16 v[6:9], v[146:149], v[194:197], v[6:9]
	v_mfma_f32_16x16x32_bf16 v[6:9], v[150:153], v[204:207], v[6:9]
	v_mfma_f32_16x16x32_bf16 v[2:5], v[154:157], v[194:197], v[2:5]
	v_mfma_f32_16x16x32_bf16 v[2:5], v[158:161], v[204:207], v[2:5]
	s_barrier
	s_add_i32 s57, 0, 0x18000
	v_add_u32_e32 v1, s57, v199
	s_add_i32 s58, 0, 0x1c000
	ds_read_b128 v[130:133], v1
	ds_read_b128 v[134:137], v1 offset:1024
	ds_read_b128 v[138:141], v1 offset:2048
	ds_read_b128 v[142:145], v1 offset:3072
	v_add_u32_e32 v1, s58, v199
	ds_read_b128 v[146:149], v1
	ds_read_b128 v[150:153], v1 offset:1024
	ds_read_b128 v[154:157], v1 offset:2048
	ds_read_b128 v[158:161], v1 offset:3072
	s_add_u32 s42, s42, 0x10000
	s_addc_u32 s43, s43, 0
	s_mov_b32 m0, s44
	v_lshl_add_u64 v[214:215], s[42:43], 0, v[178:179]
	ds_read_b128 v[162:165], v202 offset:32768
	ds_read_b128 v[166:169], v202 offset:33792
	ds_read_b128 v[170:173], v202 offset:34816
	ds_read_b128 v[174:177], v202 offset:35840
	ds_read_b128 v[186:189], v202 offset:36864
	ds_read_b128 v[190:193], v202 offset:37888
	ds_read_b128 v[194:197], v202 offset:38912
	ds_read_b128 v[204:207], v202 offset:39936
	global_load_lds_dwordx4 v[214:215], off
	v_lshl_add_u64 v[214:215], s[42:43], 0, v[182:183]
	s_mov_b32 m0, s45
	s_nop 0
	global_load_lds_dwordx4 v[214:215], off
	s_waitcnt vmcnt(8) lgkmcnt(0)
	s_barrier
	v_mfma_f32_16x16x32_bf16 v[126:129], v[130:133], v[162:165], v[126:129]
	v_mfma_f32_16x16x32_bf16 v[126:129], v[134:137], v[166:169], v[126:129]
	v_mfma_f32_16x16x32_bf16 v[122:125], v[138:141], v[162:165], v[122:125]
	v_mfma_f32_16x16x32_bf16 v[122:125], v[142:145], v[166:169], v[122:125]
	v_mfma_f32_16x16x32_bf16 v[110:113], v[130:133], v[170:173], v[110:113]
	v_mfma_f32_16x16x32_bf16 v[110:113], v[134:137], v[174:177], v[110:113]
	v_mfma_f32_16x16x32_bf16 v[106:109], v[138:141], v[170:173], v[106:109]
	v_mfma_f32_16x16x32_bf16 v[106:109], v[142:145], v[174:177], v[106:109]
	v_mfma_f32_16x16x32_bf16 v[94:97], v[130:133], v[186:189], v[94:97]
	v_mfma_f32_16x16x32_bf16 v[94:97], v[134:137], v[190:193], v[94:97]
	v_mfma_f32_16x16x32_bf16 v[90:93], v[138:141], v[186:189], v[90:93]
	v_mfma_f32_16x16x32_bf16 v[90:93], v[142:145], v[190:193], v[90:93]
	v_mfma_f32_16x16x32_bf16 v[78:81], v[130:133], v[194:197], v[78:81]
	v_mfma_f32_16x16x32_bf16 v[78:81], v[134:137], v[204:207], v[78:81]
	v_mfma_f32_16x16x32_bf16 v[74:77], v[138:141], v[194:197], v[74:77]
	v_mfma_f32_16x16x32_bf16 v[74:77], v[142:145], v[204:207], v[74:77]
	v_mfma_f32_16x16x32_bf16 v[118:121], v[146:149], v[162:165], v[118:121]
	v_mfma_f32_16x16x32_bf16 v[118:121], v[150:153], v[166:169], v[118:121]
	v_mfma_f32_16x16x32_bf16 v[114:117], v[154:157], v[162:165], v[114:117]
	v_mfma_f32_16x16x32_bf16 v[114:117], v[158:161], v[166:169], v[114:117]
	v_mfma_f32_16x16x32_bf16 v[102:105], v[146:149], v[170:173], v[102:105]
	v_mfma_f32_16x16x32_bf16 v[102:105], v[150:153], v[174:177], v[102:105]
	v_mfma_f32_16x16x32_bf16 v[98:101], v[154:157], v[170:173], v[98:101]
	v_mfma_f32_16x16x32_bf16 v[98:101], v[158:161], v[174:177], v[98:101]
	v_mfma_f32_16x16x32_bf16 v[86:89], v[146:149], v[186:189], v[86:89]
	v_mfma_f32_16x16x32_bf16 v[86:89], v[150:153], v[190:193], v[86:89]
	v_mfma_f32_16x16x32_bf16 v[82:85], v[154:157], v[186:189], v[82:85]
	v_mfma_f32_16x16x32_bf16 v[82:85], v[158:161], v[190:193], v[82:85]
	v_mfma_f32_16x16x32_bf16 v[70:73], v[146:149], v[194:197], v[70:73]
	v_mfma_f32_16x16x32_bf16 v[70:73], v[150:153], v[204:207], v[70:73]
	v_mfma_f32_16x16x32_bf16 v[66:69], v[154:157], v[194:197], v[66:69]
	v_mfma_f32_16x16x32_bf16 v[66:69], v[158:161], v[204:207], v[66:69]
	s_barrier
	s_add_i32 s42, s57, s2
	v_lshl_add_u64 v[208:209], v[208:209], 0, s[16:17]
	s_mov_b32 m0, s42
	ds_read_b128 v[162:165], v202 offset:49152
	ds_read_b128 v[166:169], v202 offset:50176
	ds_read_b128 v[170:173], v202 offset:51200
	ds_read_b128 v[174:177], v202 offset:52224
	ds_read_b128 v[186:189], v202 offset:53248
	ds_read_b128 v[190:193], v202 offset:54272
	ds_read_b128 v[194:197], v202 offset:55296
	ds_read_b128 v[204:207], v202 offset:56320
	global_load_lds_dwordx4 v[208:209], off
	s_add_i32 m0, s42, 0x2000
	s_add_u32 s40, s40, 0x208080
	v_lshl_add_u64 v[208:209], v[210:211], 0, s[16:17]
	s_addc_u32 s41, s41, 0
	s_add_i32 s42, s58, s2
	global_load_lds_dwordx4 v[208:209], off
	v_lshl_add_u64 v[208:209], s[40:41], 0, v[180:181]
	s_mov_b32 m0, s42
	s_nop 0
	global_load_lds_dwordx4 v[208:209], off
	v_lshl_add_u64 v[208:209], s[40:41], 0, v[184:185]
	s_add_i32 m0, s42, 0x2000
	s_nop 0
	global_load_lds_dwordx4 v[208:209], off
	v_lshl_add_u64 v[208:209], s[36:37], 0, v[178:179]
	s_mov_b32 m0, s47
	s_nop 0
	global_load_lds_dwordx4 v[208:209], off
	v_lshl_add_u64 v[208:209], s[36:37], 0, v[182:183]
	s_mov_b32 m0, s48
	s_nop 0
	global_load_lds_dwordx4 v[208:209], off
	s_waitcnt vmcnt(8) lgkmcnt(0)
	s_barrier
	v_mfma_f32_16x16x32_bf16 v[62:65], v[130:133], v[162:165], v[62:65]
	v_mfma_f32_16x16x32_bf16 v[62:65], v[134:137], v[166:169], v[62:65]
	v_mfma_f32_16x16x32_bf16 v[58:61], v[138:141], v[162:165], v[58:61]
	v_mfma_f32_16x16x32_bf16 v[58:61], v[142:145], v[166:169], v[58:61]
	v_mfma_f32_16x16x32_bf16 v[46:49], v[130:133], v[170:173], v[46:49]
	v_mfma_f32_16x16x32_bf16 v[46:49], v[134:137], v[174:177], v[46:49]
	v_mfma_f32_16x16x32_bf16 v[42:45], v[138:141], v[170:173], v[42:45]
	v_mfma_f32_16x16x32_bf16 v[42:45], v[142:145], v[174:177], v[42:45]
	v_mfma_f32_16x16x32_bf16 v[30:33], v[130:133], v[186:189], v[30:33]
	v_mfma_f32_16x16x32_bf16 v[30:33], v[134:137], v[190:193], v[30:33]
	v_mfma_f32_16x16x32_bf16 v[26:29], v[138:141], v[186:189], v[26:29]
	v_mfma_f32_16x16x32_bf16 v[26:29], v[142:145], v[190:193], v[26:29]
	v_mfma_f32_16x16x32_bf16 v[14:17], v[130:133], v[194:197], v[14:17]
	v_mfma_f32_16x16x32_bf16 v[14:17], v[134:137], v[204:207], v[14:17]
	v_mfma_f32_16x16x32_bf16 v[10:13], v[138:141], v[194:197], v[10:13]
	v_mfma_f32_16x16x32_bf16 v[10:13], v[142:145], v[204:207], v[10:13]
	v_mfma_f32_16x16x32_bf16 v[54:57], v[146:149], v[162:165], v[54:57]
	v_mfma_f32_16x16x32_bf16 v[54:57], v[150:153], v[166:169], v[54:57]
	v_mfma_f32_16x16x32_bf16 v[50:53], v[154:157], v[162:165], v[50:53]
	v_mfma_f32_16x16x32_bf16 v[50:53], v[158:161], v[166:169], v[50:53]
	v_mfma_f32_16x16x32_bf16 v[38:41], v[146:149], v[170:173], v[38:41]
	v_mfma_f32_16x16x32_bf16 v[38:41], v[150:153], v[174:177], v[38:41]
	v_mfma_f32_16x16x32_bf16 v[34:37], v[154:157], v[170:173], v[34:37]
	v_mfma_f32_16x16x32_bf16 v[34:37], v[158:161], v[174:177], v[34:37]
	v_mfma_f32_16x16x32_bf16 v[22:25], v[146:149], v[186:189], v[22:25]
	v_mfma_f32_16x16x32_bf16 v[22:25], v[150:153], v[190:193], v[22:25]
	v_mfma_f32_16x16x32_bf16 v[18:21], v[154:157], v[186:189], v[18:21]
	v_mfma_f32_16x16x32_bf16 v[18:21], v[158:161], v[190:193], v[18:21]
	v_mfma_f32_16x16x32_bf16 v[6:9], v[146:149], v[194:197], v[6:9]
	v_mfma_f32_16x16x32_bf16 v[6:9], v[150:153], v[204:207], v[6:9]
	v_mfma_f32_16x16x32_bf16 v[2:5], v[154:157], v[194:197], v[2:5]
	v_mfma_f32_16x16x32_bf16 v[2:5], v[158:161], v[204:207], v[2:5]
	s_barrier
	s_add_i32 s55, s55, 2
	s_add_i32 s56, s56, 0x10000
	s_cmpk_gt_u32 s55, 0x7d
	s_mov_b64 s[36:37], s[38:39]
	s_cbranch_scc0 .LBB0_519
	s_and_b64 vcc, exec, s[18:19]
	s_cbranch_vccz .LBB0_522
	s_barrier

.LBB0_612:
	ds_read_b128 v[166:169], v152
	ds_read_b128 v[170:173], v152 offset:1024
	ds_read_b128 v[174:177], v152 offset:2048
	ds_read_b128 v[178:181], v152 offset:3072
	ds_read_b128 v[182:185], v153
	ds_read_b128 v[186:189], v153 offset:1024
	ds_read_b128 v[190:193], v153 offset:2048
	ds_read_b128 v[194:197], v153 offset:3072
	s_add_u32 s26, s4, s22
	s_addc_u32 s27, s5, s23
	s_add_u32 s30, s26, 0x100
	s_addc_u32 s31, s27, 0
	s_add_u32 s28, s52, s22
	s_addc_u32 s29, s53, s23
	s_add_u32 s26, s26, 0x180
	s_addc_u32 s27, s27, 0
	s_cmpk_eq_i32 s22, 0x1f00
	s_cselect_b32 s27, s51, s27
	s_cselect_b32 s26, s50, s26
	s_cselect_b32 s29, s21, s29
	s_cselect_b32 s28, s20, s28
	s_cselect_b32 s31, s19, s31
	s_cselect_b32 s30, s18, s30
	s_mov_b32 m0, s37
	v_lshl_add_u64 v[210:211], v[148:149], 0, s[22:23]
	ds_read_b128 v[198:201], v154
	ds_read_b128 v[202:205], v154 offset:1024
	ds_read_b128 v[206:209], v154 offset:2048
	ds_read_b128 v[214:217], v154 offset:3072
	ds_read_b128 v[218:221], v154 offset:4096
	ds_read_b128 v[222:225], v154 offset:5120
	ds_read_b128 v[226:229], v154 offset:6144
	ds_read_b128 v[230:233], v154 offset:7168
	global_load_lds_dwordx4 v[210:211], off
	v_lshl_add_u64 v[210:211], v[150:151], 0, s[22:23]
	s_mov_b32 m0, s38
	s_nop 0
	global_load_lds_dwordx4 v[210:211], off
	s_waitcnt vmcnt(8) lgkmcnt(0)
	s_barrier
	v_mfma_f32_16x16x32_bf16 v[126:129], v[166:169], v[198:201], v[126:129]
	v_mfma_f32_16x16x32_bf16 v[126:129], v[170:173], v[202:205], v[126:129]
	v_mfma_f32_16x16x32_bf16 v[122:125], v[174:177], v[198:201], v[122:125]
	v_mfma_f32_16x16x32_bf16 v[122:125], v[178:181], v[202:205], v[122:125]
	v_mfma_f32_16x16x32_bf16 v[110:113], v[166:169], v[206:209], v[110:113]
	v_mfma_f32_16x16x32_bf16 v[110:113], v[170:173], v[214:217], v[110:113]
	v_mfma_f32_16x16x32_bf16 v[106:109], v[174:177], v[206:209], v[106:109]
	v_mfma_f32_16x16x32_bf16 v[106:109], v[178:181], v[214:217], v[106:109]
	v_mfma_f32_16x16x32_bf16 v[94:97], v[166:169], v[218:221], v[94:97]
	v_mfma_f32_16x16x32_bf16 v[94:97], v[170:173], v[222:225], v[94:97]
	v_mfma_f32_16x16x32_bf16 v[90:93], v[174:177], v[218:221], v[90:93]
	v_mfma_f32_16x16x32_bf16 v[90:93], v[178:181], v[222:225], v[90:93]
	v_mfma_f32_16x16x32_bf16 v[78:81], v[166:169], v[226:229], v[78:81]
	v_mfma_f32_16x16x32_bf16 v[78:81], v[170:173], v[230:233], v[78:81]
	v_mfma_f32_16x16x32_bf16 v[74:77], v[174:177], v[226:229], v[74:77]
	v_mfma_f32_16x16x32_bf16 v[74:77], v[178:181], v[230:233], v[74:77]
	v_mfma_f32_16x16x32_bf16 v[118:121], v[182:185], v[198:201], v[118:121]
	v_mfma_f32_16x16x32_bf16 v[118:121], v[186:189], v[202:205], v[118:121]
	v_mfma_f32_16x16x32_bf16 v[114:117], v[190:193], v[198:201], v[114:117]
	v_mfma_f32_16x16x32_bf16 v[114:117], v[194:197], v[202:205], v[114:117]
	v_mfma_f32_16x16x32_bf16 v[102:105], v[182:185], v[206:209], v[102:105]
	v_mfma_f32_16x16x32_bf16 v[102:105], v[186:189], v[214:217], v[102:105]
	v_mfma_f32_16x16x32_bf16 v[98:101], v[190:193], v[206:209], v[98:101]
	v_mfma_f32_16x16x32_bf16 v[98:101], v[194:197], v[214:217], v[98:101]
	v_mfma_f32_16x16x32_bf16 v[86:89], v[182:185], v[218:221], v[86:89]
	v_mfma_f32_16x16x32_bf16 v[86:89], v[186:189], v[222:225], v[86:89]
	v_mfma_f32_16x16x32_bf16 v[82:85], v[190:193], v[218:221], v[82:85]
	v_mfma_f32_16x16x32_bf16 v[82:85], v[194:197], v[222:225], v[82:85]
	v_mfma_f32_16x16x32_bf16 v[70:73], v[182:185], v[226:229], v[70:73]
	v_mfma_f32_16x16x32_bf16 v[70:73], v[186:189], v[230:233], v[70:73]
	v_mfma_f32_16x16x32_bf16 v[66:69], v[190:193], v[226:229], v[66:69]
	v_mfma_f32_16x16x32_bf16 v[66:69], v[194:197], v[230:233], v[66:69]
	s_barrier
	s_mov_b32 m0, s39
	v_lshl_add_u64 v[210:211], s[28:29], 0, v[132:133]
	s_add_u32 s56, s28, 0x108000
	ds_read_b128 v[198:201], v154 offset:16384
	ds_read_b128 v[202:205], v154 offset:17408
	ds_read_b128 v[206:209], v154 offset:18432
	ds_read_b128 v[214:217], v154 offset:19456
	ds_read_b128 v[218:221], v154 offset:20480
	ds_read_b128 v[222:225], v154 offset:21504
	ds_read_b128 v[226:229], v154 offset:22528
	ds_read_b128 v[230:233], v154 offset:23552
	global_load_lds_dwordx4 v[210:211], off
	v_lshl_add_u64 v[234:235], s[28:29], 0, v[136:137]
	s_mov_b32 m0, s40
	s_addc_u32 s57, s29, 0
	global_load_lds_dwordx4 v[234:235], off
	v_lshl_add_u64 v[236:237], s[56:57], 0, v[132:133]
	s_mov_b32 m0, s41
	s_nop 0
	global_load_lds_dwordx4 v[236:237], off
	v_lshl_add_u64 v[236:237], s[56:57], 0, v[136:137]
	s_mov_b32 m0, s42
	s_nop 0
	global_load_lds_dwordx4 v[236:237], off
	v_lshl_add_u64 v[236:237], s[30:31], 0, v[130:131]
	s_mov_b32 m0, s2
	s_nop 0
	global_load_lds_dwordx4 v[236:237], off
	v_lshl_add_u64 v[236:237], s[30:31], 0, v[134:135]
	s_mov_b32 m0, s3
	s_nop 0
	global_load_lds_dwordx4 v[236:237], off
	s_waitcnt vmcnt(8) lgkmcnt(0)
	s_barrier
	v_mfma_f32_16x16x32_bf16 v[62:65], v[166:169], v[198:201], v[62:65]
	v_mfma_f32_16x16x32_bf16 v[62:65], v[170:173], v[202:205], v[62:65]
	v_mfma_f32_16x16x32_bf16 v[58:61], v[174:177], v[198:201], v[58:61]
	v_mfma_f32_16x16x32_bf16 v[58:61], v[178:181], v[202:205], v[58:61]
	v_mfma_f32_16x16x32_bf16 v[46:49], v[166:169], v[206:209], v[46:49]
	v_mfma_f32_16x16x32_bf16 v[46:49], v[170:173], v[214:217], v[46:49]
	v_mfma_f32_16x16x32_bf16 v[42:45], v[174:177], v[206:209], v[42:45]
	v_mfma_f32_16x16x32_bf16 v[42:45], v[178:181], v[214:217], v[42:45]
	v_mfma_f32_16x16x32_bf16 v[30:33], v[166:169], v[218:221], v[30:33]
	v_mfma_f32_16x16x32_bf16 v[30:33], v[170:173], v[222:225], v[30:33]
	v_mfma_f32_16x16x32_bf16 v[26:29], v[174:177], v[218:221], v[26:29]
	v_mfma_f32_16x16x32_bf16 v[26:29], v[178:181], v[222:225], v[26:29]
	v_mfma_f32_16x16x32_bf16 v[14:17], v[166:169], v[226:229], v[14:17]
	v_mfma_f32_16x16x32_bf16 v[14:17], v[170:173], v[230:233], v[14:17]
	v_mfma_f32_16x16x32_bf16 v[10:13], v[174:177], v[226:229], v[10:13]
	v_mfma_f32_16x16x32_bf16 v[10:13], v[178:181], v[230:233], v[10:13]
	v_mfma_f32_16x16x32_bf16 v[54:57], v[182:185], v[198:201], v[54:57]
	v_mfma_f32_16x16x32_bf16 v[54:57], v[186:189], v[202:205], v[54:57]
	v_mfma_f32_16x16x32_bf16 v[50:53], v[190:193], v[198:201], v[50:53]
	v_mfma_f32_16x16x32_bf16 v[50:53], v[194:197], v[202:205], v[50:53]
	v_mfma_f32_16x16x32_bf16 v[38:41], v[182:185], v[206:209], v[38:41]
	v_mfma_f32_16x16x32_bf16 v[38:41], v[186:189], v[214:217], v[38:41]
	v_mfma_f32_16x16x32_bf16 v[34:37], v[190:193], v[206:209], v[34:37]
	v_mfma_f32_16x16x32_bf16 v[34:37], v[194:197], v[214:217], v[34:37]
	v_mfma_f32_16x16x32_bf16 v[22:25], v[182:185], v[218:221], v[22:25]
	v_mfma_f32_16x16x32_bf16 v[22:25], v[186:189], v[222:225], v[22:25]
	v_mfma_f32_16x16x32_bf16 v[18:21], v[190:193], v[218:221], v[18:21]
	v_mfma_f32_16x16x32_bf16 v[18:21], v[194:197], v[222:225], v[18:21]
	v_mfma_f32_16x16x32_bf16 v[6:9], v[182:185], v[226:229], v[6:9]
	v_mfma_f32_16x16x32_bf16 v[6:9], v[186:189], v[230:233], v[6:9]
	v_mfma_f32_16x16x32_bf16 v[2:5], v[190:193], v[226:229], v[2:5]
	v_mfma_f32_16x16x32_bf16 v[2:5], v[194:197], v[230:233], v[2:5]
	s_barrier
	ds_read_b128 v[166:169], v156
	ds_read_b128 v[170:173], v156 offset:1024
	ds_read_b128 v[174:177], v156 offset:2048
	ds_read_b128 v[178:181], v156 offset:3072
	ds_read_b128 v[182:185], v157
	ds_read_b128 v[186:189], v157 offset:1024
	ds_read_b128 v[190:193], v157 offset:2048
	ds_read_b128 v[194:197], v157 offset:3072
	s_add_u32 s30, s30, 0x108000
	s_addc_u32 s31, s31, 0
	s_mov_b32 m0, s33
	v_lshl_add_u64 v[236:237], s[30:31], 0, v[130:131]
	ds_read_b128 v[198:201], v154 offset:32768
	ds_read_b128 v[202:205], v154 offset:33792
	ds_read_b128 v[206:209], v154 offset:34816
	ds_read_b128 v[214:217], v154 offset:35840
	ds_read_b128 v[218:221], v154 offset:36864
	ds_read_b128 v[222:225], v154 offset:37888
	ds_read_b128 v[226:229], v154 offset:38912
	ds_read_b128 v[230:233], v154 offset:39936
	global_load_lds_dwordx4 v[236:237], off
	v_lshl_add_u64 v[236:237], s[30:31], 0, v[134:135]
	s_mov_b32 m0, s34
	s_nop 0
	global_load_lds_dwordx4 v[236:237], off
	s_waitcnt vmcnt(8) lgkmcnt(0)
	s_barrier
	v_mfma_f32_16x16x32_bf16 v[126:129], v[166:169], v[198:201], v[126:129]
	v_mfma_f32_16x16x32_bf16 v[126:129], v[170:173], v[202:205], v[126:129]
	v_mfma_f32_16x16x32_bf16 v[122:125], v[174:177], v[198:201], v[122:125]
	v_mfma_f32_16x16x32_bf16 v[122:125], v[178:181], v[202:205], v[122:125]
	v_mfma_f32_16x16x32_bf16 v[110:113], v[166:169], v[206:209], v[110:113]
	v_mfma_f32_16x16x32_bf16 v[110:113], v[170:173], v[214:217], v[110:113]
	v_mfma_f32_16x16x32_bf16 v[106:109], v[174:177], v[206:209], v[106:109]
	v_mfma_f32_16x16x32_bf16 v[106:109], v[178:181], v[214:217], v[106:109]
	v_mfma_f32_16x16x32_bf16 v[94:97], v[166:169], v[218:221], v[94:97]
	v_mfma_f32_16x16x32_bf16 v[94:97], v[170:173], v[222:225], v[94:97]
	v_mfma_f32_16x16x32_bf16 v[90:93], v[174:177], v[218:221], v[90:93]
	v_mfma_f32_16x16x32_bf16 v[90:93], v[178:181], v[222:225], v[90:93]
	v_mfma_f32_16x16x32_bf16 v[78:81], v[166:169], v[226:229], v[78:81]
	v_mfma_f32_16x16x32_bf16 v[78:81], v[170:173], v[230:233], v[78:81]
	v_mfma_f32_16x16x32_bf16 v[74:77], v[174:177], v[226:229], v[74:77]
	v_mfma_f32_16x16x32_bf16 v[74:77], v[178:181], v[230:233], v[74:77]
	v_mfma_f32_16x16x32_bf16 v[118:121], v[182:185], v[198:201], v[118:121]
	v_mfma_f32_16x16x32_bf16 v[118:121], v[186:189], v[202:205], v[118:121]
	v_mfma_f32_16x16x32_bf16 v[114:117], v[190:193], v[198:201], v[114:117]
	v_mfma_f32_16x16x32_bf16 v[114:117], v[194:197], v[202:205], v[114:117]
	v_mfma_f32_16x16x32_bf16 v[102:105], v[182:185], v[206:209], v[102:105]
	v_mfma_f32_16x16x32_bf16 v[102:105], v[186:189], v[214:217], v[102:105]
	v_mfma_f32_16x16x32_bf16 v[98:101], v[190:193], v[206:209], v[98:101]
	v_mfma_f32_16x16x32_bf16 v[98:101], v[194:197], v[214:217], v[98:101]
	v_mfma_f32_16x16x32_bf16 v[86:89], v[182:185], v[218:221], v[86:89]
	v_mfma_f32_16x16x32_bf16 v[86:89], v[186:189], v[222:225], v[86:89]
	v_mfma_f32_16x16x32_bf16 v[82:85], v[190:193], v[218:221], v[82:85]
	v_mfma_f32_16x16x32_bf16 v[82:85], v[194:197], v[222:225], v[82:85]
	v_mfma_f32_16x16x32_bf16 v[70:73], v[182:185], v[226:229], v[70:73]
	v_mfma_f32_16x16x32_bf16 v[70:73], v[186:189], v[230:233], v[70:73]
	v_mfma_f32_16x16x32_bf16 v[66:69], v[190:193], v[226:229], v[66:69]
	v_mfma_f32_16x16x32_bf16 v[66:69], v[194:197], v[230:233], v[66:69]
	s_barrier
	s_mov_b32 m0, s43
	v_lshl_add_u64 v[210:211], v[210:211], 0, s[14:15]
	s_add_u32 s28, s28, 0x108080
	ds_read_b128 v[198:201], v154 offset:49152
	ds_read_b128 v[202:205], v154 offset:50176
	ds_read_b128 v[206:209], v154 offset:51200
	ds_read_b128 v[214:217], v154 offset:52224
	ds_read_b128 v[218:221], v154 offset:53248
	ds_read_b128 v[222:225], v154 offset:54272
	ds_read_b128 v[226:229], v154 offset:55296
	ds_read_b128 v[230:233], v154 offset:56320
	global_load_lds_dwordx4 v[210:211], off
	v_lshl_add_u64 v[210:211], v[234:235], 0, s[14:15]
	s_mov_b32 m0, s44
	s_addc_u32 s29, s29, 0
	global_load_lds_dwordx4 v[210:211], off
	v_lshl_add_u64 v[210:211], s[28:29], 0, v[132:133]
	s_mov_b32 m0, s45
	s_nop 0
	global_load_lds_dwordx4 v[210:211], off
	v_lshl_add_u64 v[210:211], s[28:29], 0, v[136:137]
	s_mov_b32 m0, s46
	s_nop 0
	global_load_lds_dwordx4 v[210:211], off
	v_lshl_add_u64 v[210:211], s[26:27], 0, v[130:131]
	s_mov_b32 m0, s35
	s_nop 0
	global_load_lds_dwordx4 v[210:211], off
	v_lshl_add_u64 v[210:211], s[26:27], 0, v[134:135]
	s_mov_b32 m0, s36
	s_nop 0
	global_load_lds_dwordx4 v[210:211], off
	s_waitcnt vmcnt(8) lgkmcnt(0)
	s_barrier
	v_mfma_f32_16x16x32_bf16 v[62:65], v[166:169], v[198:201], v[62:65]
	v_mfma_f32_16x16x32_bf16 v[62:65], v[170:173], v[202:205], v[62:65]
	v_mfma_f32_16x16x32_bf16 v[58:61], v[174:177], v[198:201], v[58:61]
	v_mfma_f32_16x16x32_bf16 v[58:61], v[178:181], v[202:205], v[58:61]
	v_mfma_f32_16x16x32_bf16 v[46:49], v[166:169], v[206:209], v[46:49]
	v_mfma_f32_16x16x32_bf16 v[46:49], v[170:173], v[214:217], v[46:49]
	v_mfma_f32_16x16x32_bf16 v[42:45], v[174:177], v[206:209], v[42:45]
	v_mfma_f32_16x16x32_bf16 v[42:45], v[178:181], v[214:217], v[42:45]
	v_mfma_f32_16x16x32_bf16 v[30:33], v[166:169], v[218:221], v[30:33]
	v_mfma_f32_16x16x32_bf16 v[30:33], v[170:173], v[222:225], v[30:33]
	v_mfma_f32_16x16x32_bf16 v[26:29], v[174:177], v[218:221], v[26:29]
	v_mfma_f32_16x16x32_bf16 v[26:29], v[178:181], v[222:225], v[26:29]
	v_mfma_f32_16x16x32_bf16 v[14:17], v[166:169], v[226:229], v[14:17]
	v_mfma_f32_16x16x32_bf16 v[14:17], v[170:173], v[230:233], v[14:17]
	v_mfma_f32_16x16x32_bf16 v[10:13], v[174:177], v[226:229], v[10:13]
	v_mfma_f32_16x16x32_bf16 v[10:13], v[178:181], v[230:233], v[10:13]
	v_mfma_f32_16x16x32_bf16 v[54:57], v[182:185], v[198:201], v[54:57]
	v_mfma_f32_16x16x32_bf16 v[54:57], v[186:189], v[202:205], v[54:57]
	v_mfma_f32_16x16x32_bf16 v[50:53], v[190:193], v[198:201], v[50:53]
	v_mfma_f32_16x16x32_bf16 v[50:53], v[194:197], v[202:205], v[50:53]
	v_mfma_f32_16x16x32_bf16 v[38:41], v[182:185], v[206:209], v[38:41]
	v_mfma_f32_16x16x32_bf16 v[38:41], v[186:189], v[214:217], v[38:41]
	v_mfma_f32_16x16x32_bf16 v[34:37], v[190:193], v[206:209], v[34:37]
	v_mfma_f32_16x16x32_bf16 v[34:37], v[194:197], v[214:217], v[34:37]
	v_mfma_f32_16x16x32_bf16 v[22:25], v[182:185], v[218:221], v[22:25]
	v_mfma_f32_16x16x32_bf16 v[22:25], v[186:189], v[222:225], v[22:25]
	v_mfma_f32_16x16x32_bf16 v[18:21], v[190:193], v[218:221], v[18:21]
	v_mfma_f32_16x16x32_bf16 v[18:21], v[194:197], v[222:225], v[18:21]
	v_mfma_f32_16x16x32_bf16 v[6:9], v[182:185], v[226:229], v[6:9]
	v_mfma_f32_16x16x32_bf16 v[6:9], v[186:189], v[230:233], v[6:9]
	v_mfma_f32_16x16x32_bf16 v[2:5], v[190:193], v[226:229], v[2:5]
	v_mfma_f32_16x16x32_bf16 v[2:5], v[194:197], v[230:233], v[2:5]
	s_barrier
	s_add_i32 s54, s54, 2
	s_add_u32 s22, s22, 0x100
	s_addc_u32 s23, s23, 0
	s_cmp_gt_u32 s54, 61
	s_cbranch_scc0 .LBB0_612
	s_and_b64 vcc, exec, s[16:17]
	s_cbranch_vccz .LBB0_615
	s_barrier

.LBB0_844:
	s_add_i32 s35, s52, 0xfffe8000
	s_and_b32 s34, s30, 0x100
	s_and_b32 s35, s35, 0x3e0000
	s_or_b32 s34, s34, s35
	s_add_u32 s53, s28, s34
	s_addc_u32 s55, s29, 0
	s_add_u32 s34, s30, 0x100
	s_addc_u32 s35, s31, 0
	s_add_i32 s37, s52, 0xffff8000
	s_and_b32 s36, s34, 0x100
	s_and_b32 s37, s37, 0x7e0000
	s_or_b32 s36, s37, s36
	s_add_u32 s36, s28, s36
	s_addc_u32 s37, s29, 0
	s_add_u32 s54, s49, s30
	s_addc_u32 s31, s50, s31
	s_add_i32 s38, s30, 0x180
	s_and_b32 s38, s38, 0x180
	s_and_b32 s39, s52, 0x7e0000
	s_or_b32 s38, s39, s38
	s_add_u32 s56, s28, s38
	s_addc_u32 s57, s29, 0
	s_cmpk_eq_i32 s30, 0x3f00
	s_cselect_b32 s39, s1, s37
	s_cselect_b32 s38, s21, s36
	s_cselect_b32 s37, s23, s31
	s_cselect_b32 s36, s22, s54
	s_cselect_b32 s31, s48, s57
	s_cselect_b32 s30, s27, s56
	s_add_i32 s56, 0, 0x10000
	v_add_u32_e32 v124, s56, v211
	ds_read_b128 v[104:107], v124
	ds_read_b128 v[108:111], v124 offset:1024
	ds_read_b128 v[120:123], v124 offset:2048
	ds_read_b128 v[124:127], v124 offset:3072
	ds_read_b128 v[144:147], v214
	ds_read_b128 v[148:151], v214 offset:1024
	ds_read_b128 v[152:155], v214 offset:2048
	ds_read_b128 v[156:159], v214 offset:3072
	s_add_u32 s54, s53, 0x10080
	s_addc_u32 s55, s55, 0
	v_lshl_add_u64 v[200:201], s[54:55], 0, v[184:185]
	s_add_i32 m0, s3, 0xc000
	ds_read_b128 v[160:163], v215
	ds_read_b128 v[164:167], v215 offset:1024
	ds_read_b128 v[168:171], v215 offset:2048
	ds_read_b128 v[172:175], v215 offset:3072
	ds_read_b128 v[176:179], v215 offset:4096
	ds_read_b128 v[180:183], v215 offset:5120
	ds_read_b128 v[192:195], v215 offset:6144
	ds_read_b128 v[196:199], v215 offset:7168
	global_load_lds_dwordx4 v[200:201], off
	v_lshl_add_u64 v[200:201], s[54:55], 0, v[188:189]
	s_add_i32 m0, s3, 0xe000
	s_nop 0
	global_load_lds_dwordx4 v[200:201], off
	s_waitcnt vmcnt(8) lgkmcnt(0)
	s_barrier
	v_mfma_f32_16x16x32_bf16 v[140:143], v[104:107], v[160:163], v[140:143]
	v_mfma_f32_16x16x32_bf16 v[140:143], v[108:111], v[164:167], v[140:143]
	v_mfma_f32_16x16x32_bf16 v[136:139], v[120:123], v[160:163], v[136:139]
	v_mfma_f32_16x16x32_bf16 v[136:139], v[124:127], v[164:167], v[136:139]
	v_mfma_f32_16x16x32_bf16 v[116:119], v[104:107], v[168:171], v[116:119]
	v_mfma_f32_16x16x32_bf16 v[116:119], v[108:111], v[172:175], v[116:119]
	v_mfma_f32_16x16x32_bf16 v[112:115], v[120:123], v[168:171], v[112:115]
	v_mfma_f32_16x16x32_bf16 v[112:115], v[124:127], v[172:175], v[112:115]
	v_mfma_f32_16x16x32_bf16 v[92:95], v[104:107], v[176:179], v[92:95]
	v_mfma_f32_16x16x32_bf16 v[92:95], v[108:111], v[180:183], v[92:95]
	v_mfma_f32_16x16x32_bf16 v[88:91], v[120:123], v[176:179], v[88:91]
	v_mfma_f32_16x16x32_bf16 v[88:91], v[124:127], v[180:183], v[88:91]
	v_mfma_f32_16x16x32_bf16 v[76:79], v[104:107], v[192:195], v[76:79]
	v_mfma_f32_16x16x32_bf16 v[76:79], v[108:111], v[196:199], v[76:79]
	v_mfma_f32_16x16x32_bf16 v[72:75], v[120:123], v[192:195], v[72:75]
	v_mfma_f32_16x16x32_bf16 v[72:75], v[124:127], v[196:199], v[72:75]
	v_mfma_f32_16x16x32_bf16 v[132:135], v[144:147], v[160:163], v[132:135]
	v_mfma_f32_16x16x32_bf16 v[132:135], v[148:151], v[164:167], v[132:135]
	v_mfma_f32_16x16x32_bf16 v[128:131], v[152:155], v[160:163], v[128:131]
	v_mfma_f32_16x16x32_bf16 v[128:131], v[156:159], v[164:167], v[128:131]
	v_mfma_f32_16x16x32_bf16 v[100:103], v[144:147], v[168:171], v[100:103]
	v_mfma_f32_16x16x32_bf16 v[100:103], v[148:151], v[172:175], v[100:103]
	v_mfma_f32_16x16x32_bf16 v[96:99], v[152:155], v[168:171], v[96:99]
	v_mfma_f32_16x16x32_bf16 v[96:99], v[156:159], v[172:175], v[96:99]
	v_mfma_f32_16x16x32_bf16 v[84:87], v[144:147], v[176:179], v[84:87]
	v_mfma_f32_16x16x32_bf16 v[84:87], v[148:151], v[180:183], v[84:87]
	v_mfma_f32_16x16x32_bf16 v[80:83], v[152:155], v[176:179], v[80:83]
	v_mfma_f32_16x16x32_bf16 v[80:83], v[156:159], v[180:183], v[80:83]
	v_mfma_f32_16x16x32_bf16 v[68:71], v[144:147], v[192:195], v[68:71]
	v_mfma_f32_16x16x32_bf16 v[68:71], v[148:151], v[196:199], v[68:71]
	v_mfma_f32_16x16x32_bf16 v[64:67], v[152:155], v[192:195], v[64:67]
	v_mfma_f32_16x16x32_bf16 v[64:67], v[156:159], v[196:199], v[64:67]
	s_barrier
	s_add_i32 s53, s56, s2
	v_lshl_add_u64 v[200:201], s[36:37], 0, v[186:187]
	s_mov_b32 m0, s53
	ds_read_b128 v[160:163], v215 offset:16384
	ds_read_b128 v[164:167], v215 offset:17408
	ds_read_b128 v[168:171], v215 offset:18432
	ds_read_b128 v[172:175], v215 offset:19456
	ds_read_b128 v[176:179], v215 offset:20480
	ds_read_b128 v[180:183], v215 offset:21504
	ds_read_b128 v[192:195], v215 offset:22528
	ds_read_b128 v[196:199], v215 offset:23552
	global_load_lds_dwordx4 v[200:201], off
	s_add_i32 m0, s53, 0x2000
	s_add_u32 s54, s36, 0x208000
	v_lshl_add_u64 v[202:203], s[36:37], 0, v[190:191]
	s_addc_u32 s55, s37, 0
	s_add_i32 s53, s45, s2
	global_load_lds_dwordx4 v[202:203], off
	v_lshl_add_u64 v[204:205], s[54:55], 0, v[186:187]
	s_mov_b32 m0, s53
	s_nop 0
	global_load_lds_dwordx4 v[204:205], off
	v_lshl_add_u64 v[204:205], s[54:55], 0, v[190:191]
	s_add_i32 m0, s53, 0x2000
	s_nop 0
	global_load_lds_dwordx4 v[204:205], off
	v_lshl_add_u64 v[204:205], s[38:39], 0, v[184:185]
	s_mov_b32 m0, s3
	s_nop 0
	global_load_lds_dwordx4 v[204:205], off
	v_lshl_add_u64 v[204:205], s[38:39], 0, v[188:189]
	s_mov_b32 m0, s33
	s_nop 0
	global_load_lds_dwordx4 v[204:205], off
	s_waitcnt vmcnt(8) lgkmcnt(0)
	s_barrier
	v_mfma_f32_16x16x32_bf16 v[60:63], v[104:107], v[160:163], v[60:63]
	v_mfma_f32_16x16x32_bf16 v[60:63], v[108:111], v[164:167], v[60:63]
	v_mfma_f32_16x16x32_bf16 v[56:59], v[120:123], v[160:163], v[56:59]
	v_mfma_f32_16x16x32_bf16 v[56:59], v[124:127], v[164:167], v[56:59]
	v_mfma_f32_16x16x32_bf16 v[44:47], v[104:107], v[168:171], v[44:47]
	v_mfma_f32_16x16x32_bf16 v[44:47], v[108:111], v[172:175], v[44:47]
	v_mfma_f32_16x16x32_bf16 v[40:43], v[120:123], v[168:171], v[40:43]
	v_mfma_f32_16x16x32_bf16 v[40:43], v[124:127], v[172:175], v[40:43]
	v_mfma_f32_16x16x32_bf16 v[28:31], v[104:107], v[176:179], v[28:31]
	v_mfma_f32_16x16x32_bf16 v[28:31], v[108:111], v[180:183], v[28:31]
	v_mfma_f32_16x16x32_bf16 v[24:27], v[120:123], v[176:179], v[24:27]
	v_mfma_f32_16x16x32_bf16 v[24:27], v[124:127], v[180:183], v[24:27]
	v_mfma_f32_16x16x32_bf16 v[12:15], v[104:107], v[192:195], v[12:15]
	v_mfma_f32_16x16x32_bf16 v[12:15], v[108:111], v[196:199], v[12:15]
	v_mfma_f32_16x16x32_bf16 v[8:11], v[120:123], v[192:195], v[8:11]
	v_mfma_f32_16x16x32_bf16 v[8:11], v[124:127], v[196:199], v[8:11]
	v_mfma_f32_16x16x32_bf16 v[52:55], v[144:147], v[160:163], v[52:55]
	v_mfma_f32_16x16x32_bf16 v[52:55], v[148:151], v[164:167], v[52:55]
	v_mfma_f32_16x16x32_bf16 v[48:51], v[152:155], v[160:163], v[48:51]
	v_mfma_f32_16x16x32_bf16 v[48:51], v[156:159], v[164:167], v[48:51]
	v_mfma_f32_16x16x32_bf16 v[36:39], v[144:147], v[168:171], v[36:39]
	v_mfma_f32_16x16x32_bf16 v[36:39], v[148:151], v[172:175], v[36:39]
	v_mfma_f32_16x16x32_bf16 v[32:35], v[152:155], v[168:171], v[32:35]
	v_mfma_f32_16x16x32_bf16 v[32:35], v[156:159], v[172:175], v[32:35]
	v_mfma_f32_16x16x32_bf16 v[20:23], v[144:147], v[176:179], v[20:23]
	v_mfma_f32_16x16x32_bf16 v[20:23], v[148:151], v[180:183], v[20:23]
	v_mfma_f32_16x16x32_bf16 v[16:19], v[152:155], v[176:179], v[16:19]
	v_mfma_f32_16x16x32_bf16 v[16:19], v[156:159], v[180:183], v[16:19]
	v_mfma_f32_16x16x32_bf16 v[4:7], v[144:147], v[192:195], v[4:7]
	v_mfma_f32_16x16x32_bf16 v[4:7], v[148:151], v[196:199], v[4:7]
	v_mfma_f32_16x16x32_bf16 v[0:3], v[152:155], v[192:195], v[0:3]
	v_mfma_f32_16x16x32_bf16 v[0:3], v[156:159], v[196:199], v[0:3]
	s_barrier
	s_add_i32 s53, 0, 0x18000
	s_add_i32 s54, 0, 0x1c000
	v_add_u32_e32 v124, s53, v211
	v_add_u32_e32 v156, s54, v211
	ds_read_b128 v[104:107], v124
	ds_read_b128 v[108:111], v124 offset:1024
	ds_read_b128 v[120:123], v124 offset:2048
	ds_read_b128 v[124:127], v124 offset:3072
	ds_read_b128 v[144:147], v156
	ds_read_b128 v[148:151], v156 offset:1024
	ds_read_b128 v[152:155], v156 offset:2048
	ds_read_b128 v[156:159], v156 offset:3072
	s_add_u32 s38, s38, 0x10000
	s_addc_u32 s39, s39, 0
	s_mov_b32 m0, s40
	v_lshl_add_u64 v[204:205], s[38:39], 0, v[184:185]
	ds_read_b128 v[160:163], v215 offset:32768
	ds_read_b128 v[164:167], v215 offset:33792
	ds_read_b128 v[168:171], v215 offset:34816
	ds_read_b128 v[172:175], v215 offset:35840
	ds_read_b128 v[176:179], v215 offset:36864
	ds_read_b128 v[180:183], v215 offset:37888
	ds_read_b128 v[192:195], v215 offset:38912
	ds_read_b128 v[196:199], v215 offset:39936
	global_load_lds_dwordx4 v[204:205], off
	v_lshl_add_u64 v[204:205], s[38:39], 0, v[188:189]
	s_mov_b32 m0, s41
	s_nop 0
	global_load_lds_dwordx4 v[204:205], off
	s_waitcnt vmcnt(8) lgkmcnt(0)
	s_barrier
	v_mfma_f32_16x16x32_bf16 v[140:143], v[104:107], v[160:163], v[140:143]
	v_mfma_f32_16x16x32_bf16 v[140:143], v[108:111], v[164:167], v[140:143]
	v_mfma_f32_16x16x32_bf16 v[136:139], v[120:123], v[160:163], v[136:139]
	v_mfma_f32_16x16x32_bf16 v[136:139], v[124:127], v[164:167], v[136:139]
	v_mfma_f32_16x16x32_bf16 v[116:119], v[104:107], v[168:171], v[116:119]
	v_mfma_f32_16x16x32_bf16 v[116:119], v[108:111], v[172:175], v[116:119]
	v_mfma_f32_16x16x32_bf16 v[112:115], v[120:123], v[168:171], v[112:115]
	v_mfma_f32_16x16x32_bf16 v[112:115], v[124:127], v[172:175], v[112:115]
	v_mfma_f32_16x16x32_bf16 v[92:95], v[104:107], v[176:179], v[92:95]
	v_mfma_f32_16x16x32_bf16 v[92:95], v[108:111], v[180:183], v[92:95]
	v_mfma_f32_16x16x32_bf16 v[88:91], v[120:123], v[176:179], v[88:91]
	v_mfma_f32_16x16x32_bf16 v[88:91], v[124:127], v[180:183], v[88:91]
	v_mfma_f32_16x16x32_bf16 v[76:79], v[104:107], v[192:195], v[76:79]
	v_mfma_f32_16x16x32_bf16 v[76:79], v[108:111], v[196:199], v[76:79]
	v_mfma_f32_16x16x32_bf16 v[72:75], v[120:123], v[192:195], v[72:75]
	v_mfma_f32_16x16x32_bf16 v[72:75], v[124:127], v[196:199], v[72:75]
	v_mfma_f32_16x16x32_bf16 v[132:135], v[144:147], v[160:163], v[132:135]
	v_mfma_f32_16x16x32_bf16 v[132:135], v[148:151], v[164:167], v[132:135]
	v_mfma_f32_16x16x32_bf16 v[128:131], v[152:155], v[160:163], v[128:131]
	v_mfma_f32_16x16x32_bf16 v[128:131], v[156:159], v[164:167], v[128:131]
	v_mfma_f32_16x16x32_bf16 v[100:103], v[144:147], v[168:171], v[100:103]
	v_mfma_f32_16x16x32_bf16 v[100:103], v[148:151], v[172:175], v[100:103]
	v_mfma_f32_16x16x32_bf16 v[96:99], v[152:155], v[168:171], v[96:99]
	v_mfma_f32_16x16x32_bf16 v[96:99], v[156:159], v[172:175], v[96:99]
	v_mfma_f32_16x16x32_bf16 v[84:87], v[144:147], v[176:179], v[84:87]
	v_mfma_f32_16x16x32_bf16 v[84:87], v[148:151], v[180:183], v[84:87]
	v_mfma_f32_16x16x32_bf16 v[80:83], v[152:155], v[176:179], v[80:83]
	v_mfma_f32_16x16x32_bf16 v[80:83], v[156:159], v[180:183], v[80:83]
	v_mfma_f32_16x16x32_bf16 v[68:71], v[144:147], v[192:195], v[68:71]
	v_mfma_f32_16x16x32_bf16 v[68:71], v[148:151], v[196:199], v[68:71]
	v_mfma_f32_16x16x32_bf16 v[64:67], v[152:155], v[192:195], v[64:67]
	v_mfma_f32_16x16x32_bf16 v[64:67], v[156:159], v[196:199], v[64:67]
	s_barrier
	s_add_i32 s38, s53, s2
	v_lshl_add_u64 v[200:201], v[200:201], 0, s[16:17]
	s_mov_b32 m0, s38
	ds_read_b128 v[160:163], v215 offset:49152
	ds_read_b128 v[164:167], v215 offset:50176
	ds_read_b128 v[168:171], v215 offset:51200
	ds_read_b128 v[172:175], v215 offset:52224
	ds_read_b128 v[176:179], v215 offset:53248
	ds_read_b128 v[180:183], v215 offset:54272
	ds_read_b128 v[192:195], v215 offset:55296
	ds_read_b128 v[196:199], v215 offset:56320
	global_load_lds_dwordx4 v[200:201], off
	s_add_i32 m0, s38, 0x2000
	s_add_u32 s36, s36, 0x208080
	v_lshl_add_u64 v[200:201], v[202:203], 0, s[16:17]
	s_addc_u32 s37, s37, 0
	s_add_i32 s38, s54, s2
	global_load_lds_dwordx4 v[200:201], off
	v_lshl_add_u64 v[200:201], s[36:37], 0, v[186:187]
	s_mov_b32 m0, s38
	s_nop 0
	global_load_lds_dwordx4 v[200:201], off
	v_lshl_add_u64 v[200:201], s[36:37], 0, v[190:191]
	s_add_i32 m0, s38, 0x2000
	s_nop 0
	global_load_lds_dwordx4 v[200:201], off
	v_lshl_add_u64 v[200:201], s[30:31], 0, v[184:185]
	s_mov_b32 m0, s43
	s_nop 0
	global_load_lds_dwordx4 v[200:201], off
	v_lshl_add_u64 v[200:201], s[30:31], 0, v[188:189]
	s_mov_b32 m0, s44
	s_nop 0
	global_load_lds_dwordx4 v[200:201], off
	s_waitcnt vmcnt(8) lgkmcnt(0)
	s_barrier
	v_mfma_f32_16x16x32_bf16 v[60:63], v[104:107], v[160:163], v[60:63]
	v_mfma_f32_16x16x32_bf16 v[60:63], v[108:111], v[164:167], v[60:63]
	v_mfma_f32_16x16x32_bf16 v[56:59], v[120:123], v[160:163], v[56:59]
	v_mfma_f32_16x16x32_bf16 v[56:59], v[124:127], v[164:167], v[56:59]
	v_mfma_f32_16x16x32_bf16 v[44:47], v[104:107], v[168:171], v[44:47]
	v_mfma_f32_16x16x32_bf16 v[44:47], v[108:111], v[172:175], v[44:47]
	v_mfma_f32_16x16x32_bf16 v[40:43], v[120:123], v[168:171], v[40:43]
	v_mfma_f32_16x16x32_bf16 v[40:43], v[124:127], v[172:175], v[40:43]
	v_mfma_f32_16x16x32_bf16 v[28:31], v[104:107], v[176:179], v[28:31]
	v_mfma_f32_16x16x32_bf16 v[28:31], v[108:111], v[180:183], v[28:31]
	v_mfma_f32_16x16x32_bf16 v[24:27], v[120:123], v[176:179], v[24:27]
	v_mfma_f32_16x16x32_bf16 v[24:27], v[124:127], v[180:183], v[24:27]
	v_mfma_f32_16x16x32_bf16 v[12:15], v[104:107], v[192:195], v[12:15]
	v_mfma_f32_16x16x32_bf16 v[12:15], v[108:111], v[196:199], v[12:15]
	v_mfma_f32_16x16x32_bf16 v[8:11], v[120:123], v[192:195], v[8:11]
	v_mfma_f32_16x16x32_bf16 v[8:11], v[124:127], v[196:199], v[8:11]
	v_mfma_f32_16x16x32_bf16 v[52:55], v[144:147], v[160:163], v[52:55]
	v_mfma_f32_16x16x32_bf16 v[52:55], v[148:151], v[164:167], v[52:55]
	v_mfma_f32_16x16x32_bf16 v[48:51], v[152:155], v[160:163], v[48:51]
	v_mfma_f32_16x16x32_bf16 v[48:51], v[156:159], v[164:167], v[48:51]
	v_mfma_f32_16x16x32_bf16 v[36:39], v[144:147], v[168:171], v[36:39]
	v_mfma_f32_16x16x32_bf16 v[36:39], v[148:151], v[172:175], v[36:39]
	v_mfma_f32_16x16x32_bf16 v[32:35], v[152:155], v[168:171], v[32:35]
	v_mfma_f32_16x16x32_bf16 v[32:35], v[156:159], v[172:175], v[32:35]
	v_mfma_f32_16x16x32_bf16 v[20:23], v[144:147], v[176:179], v[20:23]
	v_mfma_f32_16x16x32_bf16 v[20:23], v[148:151], v[180:183], v[20:23]
	v_mfma_f32_16x16x32_bf16 v[16:19], v[152:155], v[176:179], v[16:19]
	v_mfma_f32_16x16x32_bf16 v[16:19], v[156:159], v[180:183], v[16:19]
	v_mfma_f32_16x16x32_bf16 v[4:7], v[144:147], v[192:195], v[4:7]
	v_mfma_f32_16x16x32_bf16 v[4:7], v[148:151], v[196:199], v[4:7]
	v_mfma_f32_16x16x32_bf16 v[0:3], v[152:155], v[192:195], v[0:3]
	v_mfma_f32_16x16x32_bf16 v[0:3], v[156:159], v[196:199], v[0:3]
	s_barrier
	s_add_i32 s51, s51, 2
	s_add_i32 s52, s52, 0x10000
	s_cmpk_gt_u32 s51, 0x7d
	s_mov_b64 s[30:31], s[34:35]
	s_cbranch_scc0 .LBB0_844
	s_and_b64 vcc, exec, s[18:19]
	s_cbranch_vccz .LBB0_847
	s_barrier
